# K-loops: s_sleep 1 at start of each load segment + SwiGLU loop LDS-DMA in saddr form
# speedup vs baseline: 1.0002x; 1.0002x over previous
.LBB0_147:
	s_sleep 1
	s_add_u32 s42, s40, 0xfff80080
	s_addc_u32 s43, s41, -1
	s_add_i32 s71, 0, 0x10000
	s_cmp_eq_u32 s63, 28
	s_cselect_b32 s45, s2, s43
	s_cselect_b32 s44, s5, s42
	s_cselect_b32 s43, s23, s62
	s_cselect_b32 s42, s25, s31
	s_add_i32 s73, 0, 0x14000
	s_waitcnt lgkmcnt(0)
	v_add_u32_e32 v156, s71, v169
	v_add_u32_e32 v178, s73, v169
	ds_read_b128 v[132:135], v156
	ds_read_b128 v[136:139], v156 offset:1024
	ds_read_b128 v[152:155], v156 offset:2048
	ds_read_b128 v[156:159], v156 offset:3072
	ds_read_b128 v[160:163], v178
	ds_read_b128 v[164:167], v178 offset:1024
	ds_read_b128 v[174:177], v178 offset:2048
	ds_read_b128 v[178:181], v178 offset:3072
	v_lshl_add_u64 v[202:203], s[40:41], 0, v[148:149]
	s_add_i32 m0, s53, 0xc000
	ds_read_b128 v[182:185], v171
	ds_read_b128 v[186:189], v171 offset:1024
	ds_read_b128 v[190:193], v171 offset:2048
	ds_read_b128 v[194:197], v171 offset:3072
	ds_read_b128 v[198:201], v171 offset:4096
	ds_read_b128 v[208:211], v171 offset:5120
	ds_read_b128 v[212:215], v171 offset:6144
	ds_read_b128 v[216:219], v171 offset:7168
	global_load_lds_dwordx4 v[202:203], off
	v_lshl_add_u64 v[202:203], s[40:41], 0, v[150:151]
	s_add_i32 m0, s53, 0xe000
	s_nop 0
	global_load_lds_dwordx4 v[202:203], off
	s_waitcnt vmcnt(8)
	s_waitcnt lgkmcnt(0)
	s_barrier
	s_setprio 1
	s_waitcnt lgkmcnt(0)
	v_mfma_f32_16x16x32_bf16 v[128:131], v[132:135], v[182:185], v[128:131]
	v_mfma_f32_16x16x32_bf16 v[124:127], v[152:155], v[182:185], v[124:127]
	v_mfma_f32_16x16x32_bf16 v[120:123], v[132:135], v[190:193], v[120:123]
	v_mfma_f32_16x16x32_bf16 v[112:115], v[152:155], v[190:193], v[112:115]
	v_mfma_f32_16x16x32_bf16 v[104:107], v[132:135], v[198:201], v[104:107]
	v_mfma_f32_16x16x32_bf16 v[96:99], v[152:155], v[198:201], v[96:99]
	v_mfma_f32_16x16x32_bf16 v[88:91], v[132:135], v[212:215], v[88:91]
	v_mfma_f32_16x16x32_bf16 v[80:83], v[152:155], v[212:215], v[80:83]
	v_mfma_f32_16x16x32_bf16 v[128:131], v[136:139], v[186:189], v[128:131]
	v_mfma_f32_16x16x32_bf16 v[124:127], v[156:159], v[186:189], v[124:127]
	v_mfma_f32_16x16x32_bf16 v[120:123], v[136:139], v[194:197], v[120:123]
	v_mfma_f32_16x16x32_bf16 v[112:115], v[156:159], v[194:197], v[112:115]
	v_mfma_f32_16x16x32_bf16 v[104:107], v[136:139], v[208:211], v[104:107]
	v_mfma_f32_16x16x32_bf16 v[96:99], v[156:159], v[208:211], v[96:99]
	v_mfma_f32_16x16x32_bf16 v[88:91], v[136:139], v[216:219], v[88:91]
	v_mfma_f32_16x16x32_bf16 v[80:83], v[156:159], v[216:219], v[80:83]
	s_setprio 0
	s_setprio 1
	v_mfma_f32_16x16x32_bf16 v[116:119], v[160:163], v[182:185], v[116:119]
	v_mfma_f32_16x16x32_bf16 v[108:111], v[174:177], v[182:185], v[108:111]
	v_mfma_f32_16x16x32_bf16 v[100:103], v[160:163], v[190:193], v[100:103]
	v_mfma_f32_16x16x32_bf16 v[92:95], v[174:177], v[190:193], v[92:95]
	v_mfma_f32_16x16x32_bf16 v[84:87], v[160:163], v[198:201], v[84:87]
	v_mfma_f32_16x16x32_bf16 v[76:79], v[174:177], v[198:201], v[76:79]
	v_mfma_f32_16x16x32_bf16 v[72:75], v[160:163], v[212:215], v[72:75]
	v_mfma_f32_16x16x32_bf16 v[68:71], v[174:177], v[212:215], v[68:71]
	v_mfma_f32_16x16x32_bf16 v[116:119], v[164:167], v[186:189], v[116:119]
	v_mfma_f32_16x16x32_bf16 v[108:111], v[178:181], v[186:189], v[108:111]
	v_mfma_f32_16x16x32_bf16 v[100:103], v[164:167], v[194:197], v[100:103]
	v_mfma_f32_16x16x32_bf16 v[92:95], v[178:181], v[194:197], v[92:95]
	v_mfma_f32_16x16x32_bf16 v[84:87], v[164:167], v[208:211], v[84:87]
	v_mfma_f32_16x16x32_bf16 v[76:79], v[178:181], v[208:211], v[76:79]
	v_mfma_f32_16x16x32_bf16 v[72:75], v[164:167], v[216:219], v[72:75]
	v_mfma_f32_16x16x32_bf16 v[68:71], v[178:181], v[216:219], v[68:71]
	s_setprio 0
	s_barrier
	s_sleep 1
	s_add_i32 s71, s71, s51
	v_lshl_add_u64 v[202:203], s[42:43], 0, v[2:3]
	s_mov_b32 m0, s71
	ds_read_b128 v[182:185], v171 offset:16384
	ds_read_b128 v[186:189], v171 offset:17408
	ds_read_b128 v[190:193], v171 offset:18432
	ds_read_b128 v[194:197], v171 offset:19456
	ds_read_b128 v[198:201], v171 offset:20480
	ds_read_b128 v[208:211], v171 offset:21504
	ds_read_b128 v[212:215], v171 offset:22528
	ds_read_b128 v[216:219], v171 offset:23552
	global_load_lds_dwordx4 v[202:203], off
	s_add_i32 m0, s71, 0x2000
	s_add_u32 s74, s42, 0x80000
	v_lshl_add_u64 v[204:205], s[42:43], 0, v[142:143]
	s_addc_u32 s75, s43, 0
	s_add_i32 s71, s73, s51
	global_load_lds_dwordx4 v[204:205], off
	v_lshl_add_u64 v[206:207], s[74:75], 0, v[2:3]
	s_mov_b32 m0, s71
	v_lshl_add_u64 v[220:221], s[44:45], 0, v[140:141]
	global_load_lds_dwordx4 v[206:207], off
	v_lshl_add_u64 v[206:207], s[74:75], 0, v[142:143]
	s_add_i32 m0, s71, 0x2000
	s_nop 0
	global_load_lds_dwordx4 v[206:207], off
	v_lshl_add_u64 v[206:207], s[44:45], 0, v[0:1]
	s_mov_b32 m0, s53
	s_nop 0
	global_load_lds_dwordx4 v[206:207], off
	s_mov_b32 m0, s54
	s_nop 0
	global_load_lds_dwordx4 v[220:221], off
	s_waitcnt vmcnt(8)
	s_waitcnt lgkmcnt(0)
	s_barrier
	s_setprio 1
	s_waitcnt lgkmcnt(0)
	v_mfma_f32_16x16x32_bf16 v[64:67], v[132:135], v[182:185], v[64:67]
	v_mfma_f32_16x16x32_bf16 v[60:63], v[152:155], v[182:185], v[60:63]
	v_mfma_f32_16x16x32_bf16 v[56:59], v[132:135], v[190:193], v[56:59]
	v_mfma_f32_16x16x32_bf16 v[48:51], v[152:155], v[190:193], v[48:51]
	v_mfma_f32_16x16x32_bf16 v[40:43], v[132:135], v[198:201], v[40:43]
	v_mfma_f32_16x16x32_bf16 v[32:35], v[152:155], v[198:201], v[32:35]
	v_mfma_f32_16x16x32_bf16 v[24:27], v[132:135], v[212:215], v[24:27]
	v_mfma_f32_16x16x32_bf16 v[16:19], v[152:155], v[212:215], v[16:19]
	v_mfma_f32_16x16x32_bf16 v[64:67], v[136:139], v[186:189], v[64:67]
	v_mfma_f32_16x16x32_bf16 v[60:63], v[156:159], v[186:189], v[60:63]
	v_mfma_f32_16x16x32_bf16 v[56:59], v[136:139], v[194:197], v[56:59]
	v_mfma_f32_16x16x32_bf16 v[48:51], v[156:159], v[194:197], v[48:51]
	v_mfma_f32_16x16x32_bf16 v[40:43], v[136:139], v[208:211], v[40:43]
	v_mfma_f32_16x16x32_bf16 v[32:35], v[156:159], v[208:211], v[32:35]
	v_mfma_f32_16x16x32_bf16 v[24:27], v[136:139], v[216:219], v[24:27]
	v_mfma_f32_16x16x32_bf16 v[16:19], v[156:159], v[216:219], v[16:19]
	s_setprio 0
	s_setprio 1
	v_mfma_f32_16x16x32_bf16 v[52:55], v[160:163], v[182:185], v[52:55]
	v_mfma_f32_16x16x32_bf16 v[44:47], v[174:177], v[182:185], v[44:47]
	v_mfma_f32_16x16x32_bf16 v[36:39], v[160:163], v[190:193], v[36:39]
	v_mfma_f32_16x16x32_bf16 v[28:31], v[174:177], v[190:193], v[28:31]
	v_mfma_f32_16x16x32_bf16 v[20:23], v[160:163], v[198:201], v[20:23]
	v_mfma_f32_16x16x32_bf16 v[12:15], v[174:177], v[198:201], v[12:15]
	v_mfma_f32_16x16x32_bf16 v[8:11], v[160:163], v[212:215], v[8:11]
	v_mfma_f32_16x16x32_bf16 v[4:7], v[174:177], v[212:215], v[4:7]
	v_mfma_f32_16x16x32_bf16 v[52:55], v[164:167], v[186:189], v[52:55]
	v_mfma_f32_16x16x32_bf16 v[44:47], v[178:181], v[186:189], v[44:47]
	v_mfma_f32_16x16x32_bf16 v[36:39], v[164:167], v[194:197], v[36:39]
	v_mfma_f32_16x16x32_bf16 v[28:31], v[178:181], v[194:197], v[28:31]
	v_mfma_f32_16x16x32_bf16 v[20:23], v[164:167], v[208:211], v[20:23]
	v_mfma_f32_16x16x32_bf16 v[12:15], v[178:181], v[208:211], v[12:15]
	v_mfma_f32_16x16x32_bf16 v[8:11], v[164:167], v[216:219], v[8:11]
	v_mfma_f32_16x16x32_bf16 v[4:7], v[178:181], v[216:219], v[4:7]
	s_setprio 0
	s_barrier
	s_sleep 1
	s_add_i32 s71, 0, 0x18000
	s_add_i32 s73, 0, 0x1c000
	v_add_u32_e32 v156, s71, v169
	v_add_u32_e32 v178, s73, v169
	ds_read_b128 v[132:135], v156
	ds_read_b128 v[136:139], v156 offset:1024
	ds_read_b128 v[152:155], v156 offset:2048
	ds_read_b128 v[156:159], v156 offset:3072
	ds_read_b128 v[160:163], v178
	ds_read_b128 v[164:167], v178 offset:1024
	ds_read_b128 v[174:177], v178 offset:2048
	ds_read_b128 v[178:181], v178 offset:3072
	s_add_u32 s44, s44, 0x80000
	s_addc_u32 s45, s45, 0
	s_mov_b32 m0, s55
	v_lshl_add_u64 v[222:223], s[44:45], 0, v[0:1]
	ds_read_b128 v[182:185], v171 offset:32768
	ds_read_b128 v[186:189], v171 offset:33792
	ds_read_b128 v[190:193], v171 offset:34816
	ds_read_b128 v[194:197], v171 offset:35840
	ds_read_b128 v[198:201], v171 offset:36864
	ds_read_b128 v[208:211], v171 offset:37888
	ds_read_b128 v[212:215], v171 offset:38912
	ds_read_b128 v[216:219], v171 offset:39936
	global_load_lds_dwordx4 v[222:223], off
	v_lshl_add_u64 v[222:223], s[44:45], 0, v[140:141]
	s_mov_b32 m0, s56
	s_nop 0
	global_load_lds_dwordx4 v[222:223], off
	s_waitcnt vmcnt(8)
	s_waitcnt lgkmcnt(0)
	s_barrier
	s_setprio 1
	s_waitcnt lgkmcnt(0)
	v_mfma_f32_16x16x32_bf16 v[128:131], v[132:135], v[182:185], v[128:131]
	v_mfma_f32_16x16x32_bf16 v[124:127], v[152:155], v[182:185], v[124:127]
	v_mfma_f32_16x16x32_bf16 v[120:123], v[132:135], v[190:193], v[120:123]
	v_mfma_f32_16x16x32_bf16 v[112:115], v[152:155], v[190:193], v[112:115]
	v_mfma_f32_16x16x32_bf16 v[104:107], v[132:135], v[198:201], v[104:107]
	v_mfma_f32_16x16x32_bf16 v[96:99], v[152:155], v[198:201], v[96:99]
	v_mfma_f32_16x16x32_bf16 v[88:91], v[132:135], v[212:215], v[88:91]
	v_mfma_f32_16x16x32_bf16 v[80:83], v[152:155], v[212:215], v[80:83]
	v_mfma_f32_16x16x32_bf16 v[128:131], v[136:139], v[186:189], v[128:131]
	v_mfma_f32_16x16x32_bf16 v[124:127], v[156:159], v[186:189], v[124:127]
	v_mfma_f32_16x16x32_bf16 v[120:123], v[136:139], v[194:197], v[120:123]
	v_mfma_f32_16x16x32_bf16 v[112:115], v[156:159], v[194:197], v[112:115]
	v_mfma_f32_16x16x32_bf16 v[104:107], v[136:139], v[208:211], v[104:107]
	v_mfma_f32_16x16x32_bf16 v[96:99], v[156:159], v[208:211], v[96:99]
	v_mfma_f32_16x16x32_bf16 v[88:91], v[136:139], v[216:219], v[88:91]
	v_mfma_f32_16x16x32_bf16 v[80:83], v[156:159], v[216:219], v[80:83]
	s_setprio 0
	s_setprio 1
	v_mfma_f32_16x16x32_bf16 v[116:119], v[160:163], v[182:185], v[116:119]
	v_mfma_f32_16x16x32_bf16 v[108:111], v[174:177], v[182:185], v[108:111]
	v_mfma_f32_16x16x32_bf16 v[100:103], v[160:163], v[190:193], v[100:103]
	v_mfma_f32_16x16x32_bf16 v[92:95], v[174:177], v[190:193], v[92:95]
	v_mfma_f32_16x16x32_bf16 v[84:87], v[160:163], v[198:201], v[84:87]
	v_mfma_f32_16x16x32_bf16 v[76:79], v[174:177], v[198:201], v[76:79]
	v_mfma_f32_16x16x32_bf16 v[72:75], v[160:163], v[212:215], v[72:75]
	v_mfma_f32_16x16x32_bf16 v[68:71], v[174:177], v[212:215], v[68:71]
	v_mfma_f32_16x16x32_bf16 v[116:119], v[164:167], v[186:189], v[116:119]
	v_mfma_f32_16x16x32_bf16 v[108:111], v[178:181], v[186:189], v[108:111]
	v_mfma_f32_16x16x32_bf16 v[100:103], v[164:167], v[194:197], v[100:103]
	v_mfma_f32_16x16x32_bf16 v[92:95], v[178:181], v[194:197], v[92:95]
	v_mfma_f32_16x16x32_bf16 v[84:87], v[164:167], v[208:211], v[84:87]
	v_mfma_f32_16x16x32_bf16 v[76:79], v[178:181], v[208:211], v[76:79]
	v_mfma_f32_16x16x32_bf16 v[72:75], v[164:167], v[216:219], v[72:75]
	v_mfma_f32_16x16x32_bf16 v[68:71], v[178:181], v[216:219], v[68:71]
	s_setprio 0
	s_barrier
	s_sleep 1
	s_add_i32 s44, s71, s51
	v_lshl_add_u64 v[202:203], v[202:203], 0, s[66:67]
	s_mov_b32 m0, s44
	ds_read_b128 v[182:185], v171 offset:49152
	ds_read_b128 v[186:189], v171 offset:50176
	ds_read_b128 v[190:193], v171 offset:51200
	ds_read_b128 v[194:197], v171 offset:52224
	ds_read_b128 v[198:201], v171 offset:53248
	ds_read_b128 v[208:211], v171 offset:54272
	ds_read_b128 v[212:215], v171 offset:55296
	ds_read_b128 v[216:219], v171 offset:56320
	global_load_lds_dwordx4 v[202:203], off
	s_add_i32 m0, s44, 0x2000
	s_add_u32 s42, s42, 0x80080
	v_lshl_add_u64 v[202:203], v[204:205], 0, s[66:67]
	s_addc_u32 s43, s43, 0
	s_add_i32 s44, s73, s51
	global_load_lds_dwordx4 v[202:203], off
	v_lshl_add_u64 v[202:203], s[42:43], 0, v[2:3]
	s_mov_b32 m0, s44
	s_nop 0
	global_load_lds_dwordx4 v[202:203], off
	v_lshl_add_u64 v[202:203], s[42:43], 0, v[142:143]
	s_add_i32 m0, s44, 0x2000
	s_nop 0
	global_load_lds_dwordx4 v[202:203], off
	v_lshl_add_u64 v[202:203], v[206:207], 0, s[66:67]
	s_mov_b32 m0, s65
	s_nop 0
	global_load_lds_dwordx4 v[202:203], off
	v_lshl_add_u64 v[202:203], v[220:221], 0, s[66:67]
	s_mov_b32 m0, s68
	s_nop 0
	global_load_lds_dwordx4 v[202:203], off
	s_waitcnt vmcnt(8)
	s_waitcnt lgkmcnt(0)
	s_barrier
	s_setprio 1
	s_waitcnt lgkmcnt(0)
	v_mfma_f32_16x16x32_bf16 v[64:67], v[132:135], v[182:185], v[64:67]
	v_mfma_f32_16x16x32_bf16 v[60:63], v[152:155], v[182:185], v[60:63]
	v_mfma_f32_16x16x32_bf16 v[56:59], v[132:135], v[190:193], v[56:59]
	v_mfma_f32_16x16x32_bf16 v[48:51], v[152:155], v[190:193], v[48:51]
	v_mfma_f32_16x16x32_bf16 v[40:43], v[132:135], v[198:201], v[40:43]
	v_mfma_f32_16x16x32_bf16 v[32:35], v[152:155], v[198:201], v[32:35]
	v_mfma_f32_16x16x32_bf16 v[24:27], v[132:135], v[212:215], v[24:27]
	v_mfma_f32_16x16x32_bf16 v[16:19], v[152:155], v[212:215], v[16:19]
	v_mfma_f32_16x16x32_bf16 v[64:67], v[136:139], v[186:189], v[64:67]
	v_mfma_f32_16x16x32_bf16 v[60:63], v[156:159], v[186:189], v[60:63]
	v_mfma_f32_16x16x32_bf16 v[56:59], v[136:139], v[194:197], v[56:59]
	v_mfma_f32_16x16x32_bf16 v[48:51], v[156:159], v[194:197], v[48:51]
	v_mfma_f32_16x16x32_bf16 v[40:43], v[136:139], v[208:211], v[40:43]
	v_mfma_f32_16x16x32_bf16 v[32:35], v[156:159], v[208:211], v[32:35]
	v_mfma_f32_16x16x32_bf16 v[24:27], v[136:139], v[216:219], v[24:27]
	v_mfma_f32_16x16x32_bf16 v[16:19], v[156:159], v[216:219], v[16:19]
	s_setprio 0
	s_setprio 1
	v_mfma_f32_16x16x32_bf16 v[52:55], v[160:163], v[182:185], v[52:55]
	v_mfma_f32_16x16x32_bf16 v[44:47], v[174:177], v[182:185], v[44:47]
	v_mfma_f32_16x16x32_bf16 v[36:39], v[160:163], v[190:193], v[36:39]
	v_mfma_f32_16x16x32_bf16 v[28:31], v[174:177], v[190:193], v[28:31]
	v_mfma_f32_16x16x32_bf16 v[20:23], v[160:163], v[198:201], v[20:23]
	v_mfma_f32_16x16x32_bf16 v[12:15], v[174:177], v[198:201], v[12:15]
	v_mfma_f32_16x16x32_bf16 v[8:11], v[160:163], v[212:215], v[8:11]
	v_mfma_f32_16x16x32_bf16 v[4:7], v[174:177], v[212:215], v[4:7]
	v_mfma_f32_16x16x32_bf16 v[52:55], v[164:167], v[186:189], v[52:55]
	v_mfma_f32_16x16x32_bf16 v[44:47], v[178:181], v[186:189], v[44:47]
	v_mfma_f32_16x16x32_bf16 v[36:39], v[164:167], v[194:197], v[36:39]
	v_mfma_f32_16x16x32_bf16 v[28:31], v[178:181], v[194:197], v[28:31]
	v_mfma_f32_16x16x32_bf16 v[20:23], v[164:167], v[208:211], v[20:23]
	v_mfma_f32_16x16x32_bf16 v[12:15], v[178:181], v[208:211], v[12:15]
	v_mfma_f32_16x16x32_bf16 v[8:11], v[164:167], v[216:219], v[8:11]
	v_mfma_f32_16x16x32_bf16 v[4:7], v[178:181], v[216:219], v[4:7]
	s_setprio 0
	s_barrier
	s_add_i32 s63, s63, 2
	s_add_u32 s40, s40, 0x100
	s_addc_u32 s41, s41, 0
	s_add_u32 s31, s31, 0x100
	s_addc_u32 s62, s62, 0
	s_cmp_gt_u32 s63, 29
	s_cbranch_scc0 .LBB0_147
	s_and_b64 vcc, exec, s[18:19]
	s_cbranch_vccz .LBB0_150
	s_barrier

.LBB0_211:
	s_sleep 1
	s_add_u32 s30, s28, 0xfff80080
	s_addc_u32 s31, s29, -1
	s_add_i32 s58, 0, 0x10000
	s_cmp_eq_u32 s57, 28
	s_cselect_b32 s39, s21, s31
	s_cselect_b32 s38, s53, s30
	v_add_u32_e32 v148, s58, v151
	s_cselect_b32 s31, s19, s56
	s_cselect_b32 s30, s54, s55
	s_add_i32 s60, 0, 0x14000
	ds_read_b128 v[140:143], v148
	ds_read_b128 v[144:147], v148 offset:1024
	ds_read_b128 v[156:159], v148 offset:2048
	ds_read_b128 v[160:163], v148 offset:3072
	v_add_u32_e32 v148, s60, v151
	ds_read_b128 v[164:167], v148
	ds_read_b128 v[168:171], v148 offset:1024
	ds_read_b128 v[172:175], v148 offset:2048
	ds_read_b128 v[176:179], v148 offset:3072
	s_add_i32 m0, s43, 0xc000
	ds_read_b128 v[180:183], v154
	ds_read_b128 v[184:187], v154 offset:1024
	ds_read_b128 v[188:191], v154 offset:2048
	ds_read_b128 v[192:195], v154 offset:3072
	ds_read_b128 v[196:199], v154 offset:4096
	ds_read_b128 v[200:203], v154 offset:5120
	ds_read_b128 v[208:211], v154 offset:6144
	ds_read_b128 v[212:215], v154 offset:7168
	global_load_lds_dwordx4 v136, s[28:29]
	s_add_i32 m0, s43, 0xe000
	s_nop 0
	global_load_lds_dwordx4 v138, s[28:29]
	s_waitcnt vmcnt(8)
	s_waitcnt lgkmcnt(0)
	s_barrier
	s_setprio 1
	s_waitcnt lgkmcnt(0)
	v_mfma_f32_16x16x32_bf16 v[128:131], v[140:143], v[180:183], v[128:131]
	v_mfma_f32_16x16x32_bf16 v[124:127], v[156:159], v[180:183], v[124:127]
	v_mfma_f32_16x16x32_bf16 v[112:115], v[140:143], v[188:191], v[112:115]
	v_mfma_f32_16x16x32_bf16 v[108:111], v[156:159], v[188:191], v[108:111]
	v_mfma_f32_16x16x32_bf16 v[96:99], v[140:143], v[196:199], v[96:99]
	v_mfma_f32_16x16x32_bf16 v[92:95], v[156:159], v[196:199], v[92:95]
	v_mfma_f32_16x16x32_bf16 v[80:83], v[140:143], v[208:211], v[80:83]
	v_mfma_f32_16x16x32_bf16 v[76:79], v[156:159], v[208:211], v[76:79]
	v_mfma_f32_16x16x32_bf16 v[128:131], v[144:147], v[184:187], v[128:131]
	v_mfma_f32_16x16x32_bf16 v[124:127], v[160:163], v[184:187], v[124:127]
	v_mfma_f32_16x16x32_bf16 v[112:115], v[144:147], v[192:195], v[112:115]
	v_mfma_f32_16x16x32_bf16 v[108:111], v[160:163], v[192:195], v[108:111]
	v_mfma_f32_16x16x32_bf16 v[96:99], v[144:147], v[200:203], v[96:99]
	v_mfma_f32_16x16x32_bf16 v[92:95], v[160:163], v[200:203], v[92:95]
	v_mfma_f32_16x16x32_bf16 v[80:83], v[144:147], v[212:215], v[80:83]
	v_mfma_f32_16x16x32_bf16 v[76:79], v[160:163], v[212:215], v[76:79]
	s_setprio 0
	s_setprio 1
	v_mfma_f32_16x16x32_bf16 v[120:123], v[164:167], v[180:183], v[120:123]
	v_mfma_f32_16x16x32_bf16 v[116:119], v[172:175], v[180:183], v[116:119]
	v_mfma_f32_16x16x32_bf16 v[104:107], v[164:167], v[188:191], v[104:107]
	v_mfma_f32_16x16x32_bf16 v[100:103], v[172:175], v[188:191], v[100:103]
	v_mfma_f32_16x16x32_bf16 v[88:91], v[164:167], v[196:199], v[88:91]
	v_mfma_f32_16x16x32_bf16 v[84:87], v[172:175], v[196:199], v[84:87]
	v_mfma_f32_16x16x32_bf16 v[72:75], v[164:167], v[208:211], v[72:75]
	v_mfma_f32_16x16x32_bf16 v[68:71], v[172:175], v[208:211], v[68:71]
	v_mfma_f32_16x16x32_bf16 v[120:123], v[168:171], v[184:187], v[120:123]
	v_mfma_f32_16x16x32_bf16 v[116:119], v[176:179], v[184:187], v[116:119]
	v_mfma_f32_16x16x32_bf16 v[104:107], v[168:171], v[192:195], v[104:107]
	v_mfma_f32_16x16x32_bf16 v[100:103], v[176:179], v[192:195], v[100:103]
	v_mfma_f32_16x16x32_bf16 v[88:91], v[168:171], v[200:203], v[88:91]
	v_mfma_f32_16x16x32_bf16 v[84:87], v[176:179], v[200:203], v[84:87]
	v_mfma_f32_16x16x32_bf16 v[72:75], v[168:171], v[212:215], v[72:75]
	v_mfma_f32_16x16x32_bf16 v[68:71], v[176:179], v[212:215], v[68:71]
	s_setprio 0
	s_barrier
	s_sleep 1
	s_add_i32 s58, s58, s41
	s_mov_b32 m0, s58
	ds_read_b128 v[180:183], v154 offset:16384
	ds_read_b128 v[184:187], v154 offset:17408
	ds_read_b128 v[188:191], v154 offset:18432
	ds_read_b128 v[192:195], v154 offset:19456
	ds_read_b128 v[196:199], v154 offset:20480
	ds_read_b128 v[200:203], v154 offset:21504
	ds_read_b128 v[208:211], v154 offset:22528
	ds_read_b128 v[212:215], v154 offset:23552
	global_load_lds_dwordx4 v2, s[30:31]
	s_add_i32 m0, s58, 0x2000
	s_add_u32 s62, s30, 0x80000
	s_addc_u32 s63, s31, 0
	s_add_i32 s58, s60, s41
	global_load_lds_dwordx4 v0, s[30:31]
	s_mov_b32 m0, s58
	s_nop 0
	global_load_lds_dwordx4 v2, s[62:63]
	s_add_i32 m0, s58, 0x2000
	s_nop 0
	global_load_lds_dwordx4 v0, s[62:63]
	s_mov_b32 m0, s43
	s_nop 0
	global_load_lds_dwordx4 v134, s[38:39]
	s_mov_b32 m0, s44
	s_nop 0
	global_load_lds_dwordx4 v132, s[38:39]
	s_waitcnt vmcnt(8)
	s_waitcnt lgkmcnt(0)
	s_barrier
	s_setprio 1
	s_waitcnt lgkmcnt(0)
	v_mfma_f32_16x16x32_bf16 v[64:67], v[140:143], v[180:183], v[64:67]
	v_mfma_f32_16x16x32_bf16 v[60:63], v[156:159], v[180:183], v[60:63]
	v_mfma_f32_16x16x32_bf16 v[48:51], v[140:143], v[188:191], v[48:51]
	v_mfma_f32_16x16x32_bf16 v[44:47], v[156:159], v[188:191], v[44:47]
	v_mfma_f32_16x16x32_bf16 v[32:35], v[140:143], v[196:199], v[32:35]
	v_mfma_f32_16x16x32_bf16 v[28:31], v[156:159], v[196:199], v[28:31]
	v_mfma_f32_16x16x32_bf16 v[16:19], v[140:143], v[208:211], v[16:19]
	v_mfma_f32_16x16x32_bf16 v[12:15], v[156:159], v[208:211], v[12:15]
	v_mfma_f32_16x16x32_bf16 v[64:67], v[144:147], v[184:187], v[64:67]
	v_mfma_f32_16x16x32_bf16 v[60:63], v[160:163], v[184:187], v[60:63]
	v_mfma_f32_16x16x32_bf16 v[48:51], v[144:147], v[192:195], v[48:51]
	v_mfma_f32_16x16x32_bf16 v[44:47], v[160:163], v[192:195], v[44:47]
	v_mfma_f32_16x16x32_bf16 v[32:35], v[144:147], v[200:203], v[32:35]
	v_mfma_f32_16x16x32_bf16 v[28:31], v[160:163], v[200:203], v[28:31]
	v_mfma_f32_16x16x32_bf16 v[16:19], v[144:147], v[212:215], v[16:19]
	v_mfma_f32_16x16x32_bf16 v[12:15], v[160:163], v[212:215], v[12:15]
	s_setprio 0
	s_setprio 1
	v_mfma_f32_16x16x32_bf16 v[56:59], v[164:167], v[180:183], v[56:59]
	v_mfma_f32_16x16x32_bf16 v[52:55], v[172:175], v[180:183], v[52:55]
	v_mfma_f32_16x16x32_bf16 v[40:43], v[164:167], v[188:191], v[40:43]
	v_mfma_f32_16x16x32_bf16 v[36:39], v[172:175], v[188:191], v[36:39]
	v_mfma_f32_16x16x32_bf16 v[24:27], v[164:167], v[196:199], v[24:27]
	v_mfma_f32_16x16x32_bf16 v[20:23], v[172:175], v[196:199], v[20:23]
	v_mfma_f32_16x16x32_bf16 v[8:11], v[164:167], v[208:211], v[8:11]
	v_mfma_f32_16x16x32_bf16 v[4:7], v[172:175], v[208:211], v[4:7]
	v_mfma_f32_16x16x32_bf16 v[56:59], v[168:171], v[184:187], v[56:59]
	v_mfma_f32_16x16x32_bf16 v[52:55], v[176:179], v[184:187], v[52:55]
	v_mfma_f32_16x16x32_bf16 v[40:43], v[168:171], v[192:195], v[40:43]
	v_mfma_f32_16x16x32_bf16 v[36:39], v[176:179], v[192:195], v[36:39]
	v_mfma_f32_16x16x32_bf16 v[24:27], v[168:171], v[200:203], v[24:27]
	v_mfma_f32_16x16x32_bf16 v[20:23], v[176:179], v[200:203], v[20:23]
	v_mfma_f32_16x16x32_bf16 v[8:11], v[168:171], v[212:215], v[8:11]
	v_mfma_f32_16x16x32_bf16 v[4:7], v[176:179], v[212:215], v[4:7]
	s_setprio 0
	s_barrier
	s_sleep 1
	s_add_i32 s58, 0, 0x18000
	v_add_u32_e32 v155, s58, v151
	s_add_i32 s60, 0, 0x1c000
	ds_read_b128 v[140:143], v155
	ds_read_b128 v[144:147], v155 offset:1024
	ds_read_b128 v[156:159], v155 offset:2048
	ds_read_b128 v[160:163], v155 offset:3072
	v_add_u32_e32 v155, s60, v151
	ds_read_b128 v[164:167], v155
	ds_read_b128 v[168:171], v155 offset:1024
	ds_read_b128 v[172:175], v155 offset:2048
	ds_read_b128 v[176:179], v155 offset:3072
	s_add_u32 s38, s38, 0x80000
	s_addc_u32 s39, s39, 0
	s_mov_b32 m0, s45
	ds_read_b128 v[180:183], v154 offset:32768
	ds_read_b128 v[184:187], v154 offset:33792
	ds_read_b128 v[188:191], v154 offset:34816
	ds_read_b128 v[192:195], v154 offset:35840
	ds_read_b128 v[196:199], v154 offset:36864
	ds_read_b128 v[200:203], v154 offset:37888
	ds_read_b128 v[208:211], v154 offset:38912
	ds_read_b128 v[212:215], v154 offset:39936
	global_load_lds_dwordx4 v134, s[38:39]
	s_mov_b32 m0, s47
	s_nop 0
	global_load_lds_dwordx4 v132, s[38:39]
	s_waitcnt vmcnt(8)
	s_waitcnt lgkmcnt(0)
	s_barrier
	s_setprio 1
	s_waitcnt lgkmcnt(0)
	v_mfma_f32_16x16x32_bf16 v[128:131], v[140:143], v[180:183], v[128:131]
	v_mfma_f32_16x16x32_bf16 v[124:127], v[156:159], v[180:183], v[124:127]
	v_mfma_f32_16x16x32_bf16 v[112:115], v[140:143], v[188:191], v[112:115]
	v_mfma_f32_16x16x32_bf16 v[108:111], v[156:159], v[188:191], v[108:111]
	v_mfma_f32_16x16x32_bf16 v[96:99], v[140:143], v[196:199], v[96:99]
	v_mfma_f32_16x16x32_bf16 v[92:95], v[156:159], v[196:199], v[92:95]
	v_mfma_f32_16x16x32_bf16 v[80:83], v[140:143], v[208:211], v[80:83]
	v_mfma_f32_16x16x32_bf16 v[76:79], v[156:159], v[208:211], v[76:79]
	v_mfma_f32_16x16x32_bf16 v[128:131], v[144:147], v[184:187], v[128:131]
	v_mfma_f32_16x16x32_bf16 v[124:127], v[160:163], v[184:187], v[124:127]
	v_mfma_f32_16x16x32_bf16 v[112:115], v[144:147], v[192:195], v[112:115]
	v_mfma_f32_16x16x32_bf16 v[108:111], v[160:163], v[192:195], v[108:111]
	v_mfma_f32_16x16x32_bf16 v[96:99], v[144:147], v[200:203], v[96:99]
	v_mfma_f32_16x16x32_bf16 v[92:95], v[160:163], v[200:203], v[92:95]
	v_mfma_f32_16x16x32_bf16 v[80:83], v[144:147], v[212:215], v[80:83]
	v_mfma_f32_16x16x32_bf16 v[76:79], v[160:163], v[212:215], v[76:79]
	s_setprio 0
	s_setprio 1
	v_mfma_f32_16x16x32_bf16 v[120:123], v[164:167], v[180:183], v[120:123]
	v_mfma_f32_16x16x32_bf16 v[116:119], v[172:175], v[180:183], v[116:119]
	v_mfma_f32_16x16x32_bf16 v[104:107], v[164:167], v[188:191], v[104:107]
	v_mfma_f32_16x16x32_bf16 v[100:103], v[172:175], v[188:191], v[100:103]
	v_mfma_f32_16x16x32_bf16 v[88:91], v[164:167], v[196:199], v[88:91]
	v_mfma_f32_16x16x32_bf16 v[84:87], v[172:175], v[196:199], v[84:87]
	v_mfma_f32_16x16x32_bf16 v[72:75], v[164:167], v[208:211], v[72:75]
	v_mfma_f32_16x16x32_bf16 v[68:71], v[172:175], v[208:211], v[68:71]
	v_mfma_f32_16x16x32_bf16 v[120:123], v[168:171], v[184:187], v[120:123]
	v_mfma_f32_16x16x32_bf16 v[116:119], v[176:179], v[184:187], v[116:119]
	v_mfma_f32_16x16x32_bf16 v[104:107], v[168:171], v[192:195], v[104:107]
	v_mfma_f32_16x16x32_bf16 v[100:103], v[176:179], v[192:195], v[100:103]
	v_mfma_f32_16x16x32_bf16 v[88:91], v[168:171], v[200:203], v[88:91]
	v_mfma_f32_16x16x32_bf16 v[84:87], v[176:179], v[200:203], v[84:87]
	v_mfma_f32_16x16x32_bf16 v[72:75], v[168:171], v[212:215], v[72:75]
	v_mfma_f32_16x16x32_bf16 v[68:71], v[176:179], v[212:215], v[68:71]
	s_setprio 0
	s_barrier
	s_sleep 1
	s_add_i32 s62, s58, s41
	s_add_u32 s30, s30, 0x80
	s_addc_u32 s31, s31, 0
	s_mov_b32 m0, s62
	ds_read_b128 v[180:183], v154 offset:49152
	ds_read_b128 v[184:187], v154 offset:50176
	ds_read_b128 v[188:191], v154 offset:51200
	ds_read_b128 v[192:195], v154 offset:52224
	ds_read_b128 v[196:199], v154 offset:53248
	ds_read_b128 v[200:203], v154 offset:54272
	ds_read_b128 v[208:211], v154 offset:55296
	ds_read_b128 v[212:215], v154 offset:56320
	global_load_lds_dwordx4 v2, s[30:31]
	s_add_i32 m0, s62, 0x2000
	s_nop 0
	s_add_i32 s62, s60, s41
	global_load_lds_dwordx4 v0, s[30:31]
	s_add_u32 s30, s30, 0x80000
	s_addc_u32 s31, s31, 0
	s_mov_b32 m0, s62
	s_nop 0
	global_load_lds_dwordx4 v2, s[30:31]
	s_add_i32 m0, s62, 0x2000
	s_nop 0
	global_load_lds_dwordx4 v0, s[30:31]
	s_sub_u32 s38, s38, 0x7ff80
	s_subb_u32 s39, s39, 0
	s_mov_b32 m0, s48
	s_nop 0
	global_load_lds_dwordx4 v134, s[38:39]
	s_mov_b32 m0, s49
	s_nop 0
	global_load_lds_dwordx4 v132, s[38:39]
	s_waitcnt vmcnt(8)
	s_waitcnt lgkmcnt(0)
	s_barrier
	s_setprio 1
	s_waitcnt lgkmcnt(0)
	v_mfma_f32_16x16x32_bf16 v[64:67], v[140:143], v[180:183], v[64:67]
	v_mfma_f32_16x16x32_bf16 v[60:63], v[156:159], v[180:183], v[60:63]
	v_mfma_f32_16x16x32_bf16 v[48:51], v[140:143], v[188:191], v[48:51]
	v_mfma_f32_16x16x32_bf16 v[44:47], v[156:159], v[188:191], v[44:47]
	v_mfma_f32_16x16x32_bf16 v[32:35], v[140:143], v[196:199], v[32:35]
	v_mfma_f32_16x16x32_bf16 v[28:31], v[156:159], v[196:199], v[28:31]
	v_mfma_f32_16x16x32_bf16 v[16:19], v[140:143], v[208:211], v[16:19]
	v_mfma_f32_16x16x32_bf16 v[12:15], v[156:159], v[208:211], v[12:15]
	v_mfma_f32_16x16x32_bf16 v[64:67], v[144:147], v[184:187], v[64:67]
	v_mfma_f32_16x16x32_bf16 v[60:63], v[160:163], v[184:187], v[60:63]
	v_mfma_f32_16x16x32_bf16 v[48:51], v[144:147], v[192:195], v[48:51]
	v_mfma_f32_16x16x32_bf16 v[44:47], v[160:163], v[192:195], v[44:47]
	v_mfma_f32_16x16x32_bf16 v[32:35], v[144:147], v[200:203], v[32:35]
	v_mfma_f32_16x16x32_bf16 v[28:31], v[160:163], v[200:203], v[28:31]
	v_mfma_f32_16x16x32_bf16 v[16:19], v[144:147], v[212:215], v[16:19]
	v_mfma_f32_16x16x32_bf16 v[12:15], v[160:163], v[212:215], v[12:15]
	s_setprio 0
	s_setprio 1
	v_mfma_f32_16x16x32_bf16 v[56:59], v[164:167], v[180:183], v[56:59]
	v_mfma_f32_16x16x32_bf16 v[52:55], v[172:175], v[180:183], v[52:55]
	v_mfma_f32_16x16x32_bf16 v[40:43], v[164:167], v[188:191], v[40:43]
	v_mfma_f32_16x16x32_bf16 v[36:39], v[172:175], v[188:191], v[36:39]
	v_mfma_f32_16x16x32_bf16 v[24:27], v[164:167], v[196:199], v[24:27]
	v_mfma_f32_16x16x32_bf16 v[20:23], v[172:175], v[196:199], v[20:23]
	v_mfma_f32_16x16x32_bf16 v[8:11], v[164:167], v[208:211], v[8:11]
	v_mfma_f32_16x16x32_bf16 v[4:7], v[172:175], v[208:211], v[4:7]
	v_mfma_f32_16x16x32_bf16 v[56:59], v[168:171], v[184:187], v[56:59]
	v_mfma_f32_16x16x32_bf16 v[52:55], v[176:179], v[184:187], v[52:55]
	v_mfma_f32_16x16x32_bf16 v[40:43], v[168:171], v[192:195], v[40:43]
	v_mfma_f32_16x16x32_bf16 v[36:39], v[176:179], v[192:195], v[36:39]
	v_mfma_f32_16x16x32_bf16 v[24:27], v[168:171], v[200:203], v[24:27]
	v_mfma_f32_16x16x32_bf16 v[20:23], v[176:179], v[200:203], v[20:23]
	v_mfma_f32_16x16x32_bf16 v[8:11], v[168:171], v[212:215], v[8:11]
	v_mfma_f32_16x16x32_bf16 v[4:7], v[176:179], v[212:215], v[4:7]
	s_setprio 0
	s_barrier
	s_add_i32 s57, s57, 2
	s_add_u32 s28, s28, 0x100
	s_addc_u32 s29, s29, 0
	s_add_u32 s55, s55, 0x100
	s_addc_u32 s56, s56, 0
	s_cmp_gt_u32 s57, 29
	s_cbranch_scc0 .LBB0_211
	s_and_b64 vcc, exec, s[16:17]
	s_cbranch_vccz .LBB0_214
	s_barrier

.LBB0_301:
	s_sleep 1
	s_add_u32 s18, s16, 0x100
	s_addc_u32 s19, s17, 0
	s_add_i32 s49, 0, 0x10000
	s_cmpk_eq_i32 s48, 0x54
	s_cselect_b32 s23, s13, s19
	s_cselect_b32 s22, s12, s18
	s_cselect_b32 s21, s15, s41
	s_cselect_b32 s20, s14, s40
	s_add_i32 s50, 0, 0x14000
	v_add_u32_e32 v144, s49, v219
	v_add_u32_e32 v160, s50, v219
	ds_read_b128 v[124:127], v144
	ds_read_b128 v[128:131], v144 offset:1024
	ds_read_b128 v[140:143], v144 offset:2048
	ds_read_b128 v[144:147], v144 offset:3072
	ds_read_b128 v[148:151], v160
	ds_read_b128 v[152:155], v160 offset:1024
	ds_read_b128 v[156:159], v160 offset:2048
	ds_read_b128 v[160:163], v160 offset:3072
	v_lshl_add_u64 v[204:205], s[16:17], 0, v[192:193]
	s_add_i32 m0, s28, 0xc000
	ds_read_b128 v[164:167], v221
	ds_read_b128 v[168:171], v221 offset:1024
	ds_read_b128 v[172:175], v221 offset:2048
	ds_read_b128 v[176:179], v221 offset:3072
	ds_read_b128 v[180:183], v221 offset:4096
	ds_read_b128 v[184:187], v221 offset:5120
	ds_read_b128 v[196:199], v221 offset:6144
	ds_read_b128 v[200:203], v221 offset:7168
	global_load_lds_dwordx4 v[204:205], off
	v_lshl_add_u64 v[204:205], s[16:17], 0, v[194:195]
	s_add_i32 m0, s28, 0xe000
	s_nop 0
	global_load_lds_dwordx4 v[204:205], off
	s_waitcnt vmcnt(8)
	s_waitcnt lgkmcnt(0)
	s_barrier
	s_setprio 1
	s_waitcnt lgkmcnt(0)
	v_mfma_f32_16x16x32_bf16 v[136:139], v[124:127], v[164:167], v[136:139]
	v_mfma_f32_16x16x32_bf16 v[132:135], v[140:143], v[164:167], v[132:135]
	v_mfma_f32_16x16x32_bf16 v[112:115], v[124:127], v[172:175], v[112:115]
	v_mfma_f32_16x16x32_bf16 v[108:111], v[140:143], v[172:175], v[108:111]
	v_mfma_f32_16x16x32_bf16 v[96:99], v[124:127], v[180:183], v[96:99]
	v_mfma_f32_16x16x32_bf16 v[92:95], v[140:143], v[180:183], v[92:95]
	v_mfma_f32_16x16x32_bf16 v[80:83], v[124:127], v[196:199], v[80:83]
	v_mfma_f32_16x16x32_bf16 v[76:79], v[140:143], v[196:199], v[76:79]
	v_mfma_f32_16x16x32_bf16 v[136:139], v[128:131], v[168:171], v[136:139]
	v_mfma_f32_16x16x32_bf16 v[132:135], v[144:147], v[168:171], v[132:135]
	v_mfma_f32_16x16x32_bf16 v[112:115], v[128:131], v[176:179], v[112:115]
	v_mfma_f32_16x16x32_bf16 v[108:111], v[144:147], v[176:179], v[108:111]
	v_mfma_f32_16x16x32_bf16 v[96:99], v[128:131], v[184:187], v[96:99]
	v_mfma_f32_16x16x32_bf16 v[92:95], v[144:147], v[184:187], v[92:95]
	v_mfma_f32_16x16x32_bf16 v[80:83], v[128:131], v[200:203], v[80:83]
	v_mfma_f32_16x16x32_bf16 v[76:79], v[144:147], v[200:203], v[76:79]
	s_setprio 0
	s_setprio 1
	v_mfma_f32_16x16x32_bf16 v[120:123], v[148:151], v[164:167], v[120:123]
	v_mfma_f32_16x16x32_bf16 v[116:119], v[156:159], v[164:167], v[116:119]
	v_mfma_f32_16x16x32_bf16 v[104:107], v[148:151], v[172:175], v[104:107]
	v_mfma_f32_16x16x32_bf16 v[100:103], v[156:159], v[172:175], v[100:103]
	v_mfma_f32_16x16x32_bf16 v[88:91], v[148:151], v[180:183], v[88:91]
	v_mfma_f32_16x16x32_bf16 v[84:87], v[156:159], v[180:183], v[84:87]
	v_mfma_f32_16x16x32_bf16 v[72:75], v[148:151], v[196:199], v[72:75]
	v_mfma_f32_16x16x32_bf16 v[68:71], v[156:159], v[196:199], v[68:71]
	v_mfma_f32_16x16x32_bf16 v[120:123], v[152:155], v[168:171], v[120:123]
	v_mfma_f32_16x16x32_bf16 v[116:119], v[160:163], v[168:171], v[116:119]
	v_mfma_f32_16x16x32_bf16 v[104:107], v[152:155], v[176:179], v[104:107]
	v_mfma_f32_16x16x32_bf16 v[100:103], v[160:163], v[176:179], v[100:103]
	v_mfma_f32_16x16x32_bf16 v[88:91], v[152:155], v[184:187], v[88:91]
	v_mfma_f32_16x16x32_bf16 v[84:87], v[160:163], v[184:187], v[84:87]
	v_mfma_f32_16x16x32_bf16 v[72:75], v[152:155], v[200:203], v[72:75]
	v_mfma_f32_16x16x32_bf16 v[68:71], v[160:163], v[200:203], v[68:71]
	s_setprio 0
	s_barrier
	s_sleep 1
	s_add_i32 s16, s49, s2
	v_lshl_add_u64 v[204:205], s[20:21], 0, v[2:3]
	s_mov_b32 m0, s16
	ds_read_b128 v[164:167], v221 offset:16384
	ds_read_b128 v[168:171], v221 offset:17408
	ds_read_b128 v[172:175], v221 offset:18432
	ds_read_b128 v[176:179], v221 offset:19456
	ds_read_b128 v[180:183], v221 offset:20480
	ds_read_b128 v[184:187], v221 offset:21504
	ds_read_b128 v[196:199], v221 offset:22528
	ds_read_b128 v[200:203], v221 offset:23552
	global_load_lds_dwordx4 v[204:205], off
	s_add_i32 m0, s16, 0x2000
	s_add_u32 s16, s20, 0x160000
	v_lshl_add_u64 v[206:207], s[20:21], 0, v[190:191]
	s_addc_u32 s17, s21, 0
	s_add_i32 s49, s50, s2
	global_load_lds_dwordx4 v[206:207], off
	v_lshl_add_u64 v[208:209], s[16:17], 0, v[2:3]
	s_mov_b32 m0, s49
	v_lshl_add_u64 v[210:211], s[22:23], 0, v[188:189]
	global_load_lds_dwordx4 v[208:209], off
	v_lshl_add_u64 v[208:209], s[16:17], 0, v[190:191]
	s_add_i32 m0, s49, 0x2000
	s_nop 0
	global_load_lds_dwordx4 v[208:209], off
	v_lshl_add_u64 v[208:209], s[22:23], 0, v[0:1]
	s_mov_b32 m0, s28
	s_nop 0
	global_load_lds_dwordx4 v[208:209], off
	s_mov_b32 m0, s29
	s_nop 0
	global_load_lds_dwordx4 v[210:211], off
	s_waitcnt vmcnt(8)
	s_waitcnt lgkmcnt(0)
	s_barrier
	s_setprio 1
	s_waitcnt lgkmcnt(0)
	v_mfma_f32_16x16x32_bf16 v[64:67], v[124:127], v[164:167], v[64:67]
	v_mfma_f32_16x16x32_bf16 v[60:63], v[140:143], v[164:167], v[60:63]
	v_mfma_f32_16x16x32_bf16 v[48:51], v[124:127], v[172:175], v[48:51]
	v_mfma_f32_16x16x32_bf16 v[44:47], v[140:143], v[172:175], v[44:47]
	v_mfma_f32_16x16x32_bf16 v[32:35], v[124:127], v[180:183], v[32:35]
	v_mfma_f32_16x16x32_bf16 v[28:31], v[140:143], v[180:183], v[28:31]
	v_mfma_f32_16x16x32_bf16 v[16:19], v[124:127], v[196:199], v[16:19]
	v_mfma_f32_16x16x32_bf16 v[12:15], v[140:143], v[196:199], v[12:15]
	v_mfma_f32_16x16x32_bf16 v[64:67], v[128:131], v[168:171], v[64:67]
	v_mfma_f32_16x16x32_bf16 v[60:63], v[144:147], v[168:171], v[60:63]
	v_mfma_f32_16x16x32_bf16 v[48:51], v[128:131], v[176:179], v[48:51]
	v_mfma_f32_16x16x32_bf16 v[44:47], v[144:147], v[176:179], v[44:47]
	v_mfma_f32_16x16x32_bf16 v[32:35], v[128:131], v[184:187], v[32:35]
	v_mfma_f32_16x16x32_bf16 v[28:31], v[144:147], v[184:187], v[28:31]
	v_mfma_f32_16x16x32_bf16 v[16:19], v[128:131], v[200:203], v[16:19]
	v_mfma_f32_16x16x32_bf16 v[12:15], v[144:147], v[200:203], v[12:15]
	s_setprio 0
	s_setprio 1
	v_mfma_f32_16x16x32_bf16 v[56:59], v[148:151], v[164:167], v[56:59]
	v_mfma_f32_16x16x32_bf16 v[52:55], v[156:159], v[164:167], v[52:55]
	v_mfma_f32_16x16x32_bf16 v[40:43], v[148:151], v[172:175], v[40:43]
	v_mfma_f32_16x16x32_bf16 v[36:39], v[156:159], v[172:175], v[36:39]
	v_mfma_f32_16x16x32_bf16 v[24:27], v[148:151], v[180:183], v[24:27]
	v_mfma_f32_16x16x32_bf16 v[20:23], v[156:159], v[180:183], v[20:23]
	v_mfma_f32_16x16x32_bf16 v[8:11], v[148:151], v[196:199], v[8:11]
	v_mfma_f32_16x16x32_bf16 v[4:7], v[156:159], v[196:199], v[4:7]
	v_mfma_f32_16x16x32_bf16 v[56:59], v[152:155], v[168:171], v[56:59]
	v_mfma_f32_16x16x32_bf16 v[52:55], v[160:163], v[168:171], v[52:55]
	v_mfma_f32_16x16x32_bf16 v[40:43], v[152:155], v[176:179], v[40:43]
	v_mfma_f32_16x16x32_bf16 v[36:39], v[160:163], v[176:179], v[36:39]
	v_mfma_f32_16x16x32_bf16 v[24:27], v[152:155], v[184:187], v[24:27]
	v_mfma_f32_16x16x32_bf16 v[20:23], v[160:163], v[184:187], v[20:23]
	v_mfma_f32_16x16x32_bf16 v[8:11], v[152:155], v[200:203], v[8:11]
	v_mfma_f32_16x16x32_bf16 v[4:7], v[160:163], v[200:203], v[4:7]
	s_setprio 0
	s_barrier
	s_sleep 1
	s_add_i32 s49, 0, 0x18000
	s_add_i32 s50, 0, 0x1c000
	v_add_u32_e32 v144, s49, v219
	v_add_u32_e32 v160, s50, v219
	ds_read_b128 v[124:127], v144
	ds_read_b128 v[128:131], v144 offset:1024
	ds_read_b128 v[140:143], v144 offset:2048
	ds_read_b128 v[144:147], v144 offset:3072
	ds_read_b128 v[148:151], v160
	ds_read_b128 v[152:155], v160 offset:1024
	ds_read_b128 v[156:159], v160 offset:2048
	ds_read_b128 v[160:163], v160 offset:3072
	s_add_u32 s16, s22, 0x160000
	s_addc_u32 s17, s23, 0
	s_mov_b32 m0, s30
	v_lshl_add_u64 v[212:213], s[16:17], 0, v[0:1]
	ds_read_b128 v[164:167], v221 offset:32768
	ds_read_b128 v[168:171], v221 offset:33792
	ds_read_b128 v[172:175], v221 offset:34816
	ds_read_b128 v[176:179], v221 offset:35840
	ds_read_b128 v[180:183], v221 offset:36864
	ds_read_b128 v[184:187], v221 offset:37888
	ds_read_b128 v[196:199], v221 offset:38912
	ds_read_b128 v[200:203], v221 offset:39936
	global_load_lds_dwordx4 v[212:213], off
	v_lshl_add_u64 v[212:213], s[16:17], 0, v[188:189]
	s_mov_b32 m0, s31
	s_nop 0
	global_load_lds_dwordx4 v[212:213], off
	s_waitcnt vmcnt(8)
	s_waitcnt lgkmcnt(0)
	s_barrier
	s_setprio 1
	s_waitcnt lgkmcnt(0)
	v_mfma_f32_16x16x32_bf16 v[136:139], v[124:127], v[164:167], v[136:139]
	v_mfma_f32_16x16x32_bf16 v[132:135], v[140:143], v[164:167], v[132:135]
	v_mfma_f32_16x16x32_bf16 v[112:115], v[124:127], v[172:175], v[112:115]
	v_mfma_f32_16x16x32_bf16 v[108:111], v[140:143], v[172:175], v[108:111]
	v_mfma_f32_16x16x32_bf16 v[96:99], v[124:127], v[180:183], v[96:99]
	v_mfma_f32_16x16x32_bf16 v[92:95], v[140:143], v[180:183], v[92:95]
	v_mfma_f32_16x16x32_bf16 v[80:83], v[124:127], v[196:199], v[80:83]
	v_mfma_f32_16x16x32_bf16 v[76:79], v[140:143], v[196:199], v[76:79]
	v_mfma_f32_16x16x32_bf16 v[136:139], v[128:131], v[168:171], v[136:139]
	v_mfma_f32_16x16x32_bf16 v[132:135], v[144:147], v[168:171], v[132:135]
	v_mfma_f32_16x16x32_bf16 v[112:115], v[128:131], v[176:179], v[112:115]
	v_mfma_f32_16x16x32_bf16 v[108:111], v[144:147], v[176:179], v[108:111]
	v_mfma_f32_16x16x32_bf16 v[96:99], v[128:131], v[184:187], v[96:99]
	v_mfma_f32_16x16x32_bf16 v[92:95], v[144:147], v[184:187], v[92:95]
	v_mfma_f32_16x16x32_bf16 v[80:83], v[128:131], v[200:203], v[80:83]
	v_mfma_f32_16x16x32_bf16 v[76:79], v[144:147], v[200:203], v[76:79]
	s_setprio 0
	s_setprio 1
	v_mfma_f32_16x16x32_bf16 v[120:123], v[148:151], v[164:167], v[120:123]
	v_mfma_f32_16x16x32_bf16 v[116:119], v[156:159], v[164:167], v[116:119]
	v_mfma_f32_16x16x32_bf16 v[104:107], v[148:151], v[172:175], v[104:107]
	v_mfma_f32_16x16x32_bf16 v[100:103], v[156:159], v[172:175], v[100:103]
	v_mfma_f32_16x16x32_bf16 v[88:91], v[148:151], v[180:183], v[88:91]
	v_mfma_f32_16x16x32_bf16 v[84:87], v[156:159], v[180:183], v[84:87]
	v_mfma_f32_16x16x32_bf16 v[72:75], v[148:151], v[196:199], v[72:75]
	v_mfma_f32_16x16x32_bf16 v[68:71], v[156:159], v[196:199], v[68:71]
	v_mfma_f32_16x16x32_bf16 v[120:123], v[152:155], v[168:171], v[120:123]
	v_mfma_f32_16x16x32_bf16 v[116:119], v[160:163], v[168:171], v[116:119]
	v_mfma_f32_16x16x32_bf16 v[104:107], v[152:155], v[176:179], v[104:107]
	v_mfma_f32_16x16x32_bf16 v[100:103], v[160:163], v[176:179], v[100:103]
	v_mfma_f32_16x16x32_bf16 v[88:91], v[152:155], v[184:187], v[88:91]
	v_mfma_f32_16x16x32_bf16 v[84:87], v[160:163], v[184:187], v[84:87]
	v_mfma_f32_16x16x32_bf16 v[72:75], v[152:155], v[200:203], v[72:75]
	v_mfma_f32_16x16x32_bf16 v[68:71], v[160:163], v[200:203], v[68:71]
	s_setprio 0
	s_barrier
	s_sleep 1
	s_add_i32 s16, s49, s2
	v_lshl_add_u64 v[204:205], v[204:205], 0, s[66:67]
	s_mov_b32 m0, s16
	ds_read_b128 v[164:167], v221 offset:49152
	ds_read_b128 v[168:171], v221 offset:50176
	ds_read_b128 v[172:175], v221 offset:51200
	ds_read_b128 v[176:179], v221 offset:52224
	ds_read_b128 v[180:183], v221 offset:53248
	ds_read_b128 v[184:187], v221 offset:54272
	ds_read_b128 v[196:199], v221 offset:55296
	ds_read_b128 v[200:203], v221 offset:56320
	global_load_lds_dwordx4 v[204:205], off
	s_add_i32 m0, s16, 0x2000
	s_add_u32 s16, s20, 0x160080
	v_lshl_add_u64 v[204:205], v[206:207], 0, s[66:67]
	s_addc_u32 s17, s21, 0
	s_add_i32 s20, s50, s2
	global_load_lds_dwordx4 v[204:205], off
	v_lshl_add_u64 v[204:205], s[16:17], 0, v[2:3]
	s_mov_b32 m0, s20
	s_nop 0
	global_load_lds_dwordx4 v[204:205], off
	v_lshl_add_u64 v[204:205], s[16:17], 0, v[190:191]
	s_add_i32 m0, s20, 0x2000
	s_nop 0
	global_load_lds_dwordx4 v[204:205], off
	v_lshl_add_u64 v[204:205], v[208:209], 0, s[66:67]
	s_mov_b32 m0, s34
	s_nop 0
	global_load_lds_dwordx4 v[204:205], off
	v_lshl_add_u64 v[204:205], v[210:211], 0, s[66:67]
	s_mov_b32 m0, s35
	s_nop 0
	global_load_lds_dwordx4 v[204:205], off
	s_waitcnt vmcnt(8)
	s_waitcnt lgkmcnt(0)
	s_barrier
	s_setprio 1
	s_waitcnt lgkmcnt(0)
	v_mfma_f32_16x16x32_bf16 v[64:67], v[124:127], v[164:167], v[64:67]
	v_mfma_f32_16x16x32_bf16 v[60:63], v[140:143], v[164:167], v[60:63]
	v_mfma_f32_16x16x32_bf16 v[48:51], v[124:127], v[172:175], v[48:51]
	v_mfma_f32_16x16x32_bf16 v[44:47], v[140:143], v[172:175], v[44:47]
	v_mfma_f32_16x16x32_bf16 v[32:35], v[124:127], v[180:183], v[32:35]
	v_mfma_f32_16x16x32_bf16 v[28:31], v[140:143], v[180:183], v[28:31]
	v_mfma_f32_16x16x32_bf16 v[16:19], v[124:127], v[196:199], v[16:19]
	v_mfma_f32_16x16x32_bf16 v[12:15], v[140:143], v[196:199], v[12:15]
	v_mfma_f32_16x16x32_bf16 v[64:67], v[128:131], v[168:171], v[64:67]
	v_mfma_f32_16x16x32_bf16 v[60:63], v[144:147], v[168:171], v[60:63]
	v_mfma_f32_16x16x32_bf16 v[48:51], v[128:131], v[176:179], v[48:51]
	v_mfma_f32_16x16x32_bf16 v[44:47], v[144:147], v[176:179], v[44:47]
	v_mfma_f32_16x16x32_bf16 v[32:35], v[128:131], v[184:187], v[32:35]
	v_mfma_f32_16x16x32_bf16 v[28:31], v[144:147], v[184:187], v[28:31]
	v_mfma_f32_16x16x32_bf16 v[16:19], v[128:131], v[200:203], v[16:19]
	v_mfma_f32_16x16x32_bf16 v[12:15], v[144:147], v[200:203], v[12:15]
	s_setprio 0
	s_setprio 1
	v_mfma_f32_16x16x32_bf16 v[56:59], v[148:151], v[164:167], v[56:59]
	v_mfma_f32_16x16x32_bf16 v[52:55], v[156:159], v[164:167], v[52:55]
	v_mfma_f32_16x16x32_bf16 v[40:43], v[148:151], v[172:175], v[40:43]
	v_mfma_f32_16x16x32_bf16 v[36:39], v[156:159], v[172:175], v[36:39]
	v_mfma_f32_16x16x32_bf16 v[24:27], v[148:151], v[180:183], v[24:27]
	v_mfma_f32_16x16x32_bf16 v[20:23], v[156:159], v[180:183], v[20:23]
	v_mfma_f32_16x16x32_bf16 v[8:11], v[148:151], v[196:199], v[8:11]
	v_mfma_f32_16x16x32_bf16 v[4:7], v[156:159], v[196:199], v[4:7]
	v_mfma_f32_16x16x32_bf16 v[56:59], v[152:155], v[168:171], v[56:59]
	v_mfma_f32_16x16x32_bf16 v[52:55], v[160:163], v[168:171], v[52:55]
	v_mfma_f32_16x16x32_bf16 v[40:43], v[152:155], v[176:179], v[40:43]
	v_mfma_f32_16x16x32_bf16 v[36:39], v[160:163], v[176:179], v[36:39]
	v_mfma_f32_16x16x32_bf16 v[24:27], v[152:155], v[184:187], v[24:27]
	v_mfma_f32_16x16x32_bf16 v[20:23], v[160:163], v[184:187], v[20:23]
	v_mfma_f32_16x16x32_bf16 v[8:11], v[152:155], v[200:203], v[8:11]
	v_mfma_f32_16x16x32_bf16 v[4:7], v[160:163], v[200:203], v[4:7]
	s_setprio 0
	s_barrier
	s_add_i32 s48, s48, 2
	s_add_u32 s40, s40, 0x100
	s_addc_u32 s41, s41, 0
	s_cmpk_gt_u32 s48, 0x55
	s_mov_b64 s[16:17], s[18:19]
	s_cbranch_scc0 .LBB0_301
	s_and_b64 vcc, exec, s[10:11]
	s_cbranch_vccz .LBB0_304
	s_barrier

.LBB0_347:
	s_sleep 1
	s_add_u32 s16, s14, 0x100
	s_addc_u32 s17, s15, 0
	s_add_i32 s44, 0, 0x10000
	s_cmpk_eq_i32 s43, 0x54
	s_cselect_b32 s21, s11, s17
	s_cselect_b32 s20, s10, s16
	s_cselect_b32 s19, s13, s39
	s_cselect_b32 s18, s12, s38
	s_add_i32 s45, 0, 0x14000
	v_add_u32_e32 v144, s44, v236
	v_add_u32_e32 v160, s45, v236
	ds_read_b128 v[132:135], v144
	ds_read_b128 v[136:139], v144 offset:1024
	ds_read_b128 v[140:143], v144 offset:2048
	ds_read_b128 v[144:147], v144 offset:3072
	ds_read_b128 v[148:151], v160
	ds_read_b128 v[152:155], v160 offset:1024
	ds_read_b128 v[156:159], v160 offset:2048
	ds_read_b128 v[160:163], v160 offset:3072
	v_lshl_add_u64 v[204:205], s[14:15], 0, v[200:201]
	s_add_i32 m0, s23, 0xc000
	ds_read_b128 v[164:167], v238
	ds_read_b128 v[168:171], v238 offset:1024
	ds_read_b128 v[172:175], v238 offset:2048
	ds_read_b128 v[176:179], v238 offset:3072
	ds_read_b128 v[180:183], v238 offset:4096
	ds_read_b128 v[184:187], v238 offset:5120
	ds_read_b128 v[188:191], v238 offset:6144
	ds_read_b128 v[192:195], v238 offset:7168
	global_load_lds_dwordx4 v[204:205], off
	v_lshl_add_u64 v[204:205], s[14:15], 0, v[202:203]
	s_add_i32 m0, s23, 0xe000
	s_nop 0
	global_load_lds_dwordx4 v[204:205], off
	s_waitcnt vmcnt(8)
	s_waitcnt lgkmcnt(0)
	s_barrier
	s_setprio 1
	s_waitcnt lgkmcnt(0)
	v_mfma_f32_16x16x32_bf16 v[128:131], v[132:135], v[164:167], v[128:131]
	v_mfma_f32_16x16x32_bf16 v[124:127], v[140:143], v[164:167], v[124:127]
	v_mfma_f32_16x16x32_bf16 v[116:119], v[132:135], v[172:175], v[116:119]
	v_mfma_f32_16x16x32_bf16 v[108:111], v[140:143], v[172:175], v[108:111]
	v_mfma_f32_16x16x32_bf16 v[100:103], v[132:135], v[180:183], v[100:103]
	v_mfma_f32_16x16x32_bf16 v[92:95], v[140:143], v[180:183], v[92:95]
	v_mfma_f32_16x16x32_bf16 v[84:87], v[132:135], v[188:191], v[84:87]
	v_mfma_f32_16x16x32_bf16 v[76:79], v[140:143], v[188:191], v[76:79]
	v_mfma_f32_16x16x32_bf16 v[128:131], v[136:139], v[168:171], v[128:131]
	v_mfma_f32_16x16x32_bf16 v[124:127], v[144:147], v[168:171], v[124:127]
	v_mfma_f32_16x16x32_bf16 v[116:119], v[136:139], v[176:179], v[116:119]
	v_mfma_f32_16x16x32_bf16 v[108:111], v[144:147], v[176:179], v[108:111]
	v_mfma_f32_16x16x32_bf16 v[100:103], v[136:139], v[184:187], v[100:103]
	v_mfma_f32_16x16x32_bf16 v[92:95], v[144:147], v[184:187], v[92:95]
	v_mfma_f32_16x16x32_bf16 v[84:87], v[136:139], v[192:195], v[84:87]
	v_mfma_f32_16x16x32_bf16 v[76:79], v[144:147], v[192:195], v[76:79]
	s_setprio 0
	s_setprio 1
	v_mfma_f32_16x16x32_bf16 v[120:123], v[148:151], v[164:167], v[120:123]
	v_mfma_f32_16x16x32_bf16 v[112:115], v[156:159], v[164:167], v[112:115]
	v_mfma_f32_16x16x32_bf16 v[104:107], v[148:151], v[172:175], v[104:107]
	v_mfma_f32_16x16x32_bf16 v[96:99], v[156:159], v[172:175], v[96:99]
	v_mfma_f32_16x16x32_bf16 v[88:91], v[148:151], v[180:183], v[88:91]
	v_mfma_f32_16x16x32_bf16 v[80:83], v[156:159], v[180:183], v[80:83]
	v_mfma_f32_16x16x32_bf16 v[72:75], v[148:151], v[188:191], v[72:75]
	v_mfma_f32_16x16x32_bf16 v[68:71], v[156:159], v[188:191], v[68:71]
	v_mfma_f32_16x16x32_bf16 v[120:123], v[152:155], v[168:171], v[120:123]
	v_mfma_f32_16x16x32_bf16 v[112:115], v[160:163], v[168:171], v[112:115]
	v_mfma_f32_16x16x32_bf16 v[104:107], v[152:155], v[176:179], v[104:107]
	v_mfma_f32_16x16x32_bf16 v[96:99], v[160:163], v[176:179], v[96:99]
	v_mfma_f32_16x16x32_bf16 v[88:91], v[152:155], v[184:187], v[88:91]
	v_mfma_f32_16x16x32_bf16 v[80:83], v[160:163], v[184:187], v[80:83]
	v_mfma_f32_16x16x32_bf16 v[72:75], v[152:155], v[192:195], v[72:75]
	v_mfma_f32_16x16x32_bf16 v[68:71], v[160:163], v[192:195], v[68:71]
	s_setprio 0
	s_barrier
	s_sleep 1
	s_add_i32 s14, s44, s22
	v_lshl_add_u64 v[204:205], s[18:19], 0, v[2:3]
	s_mov_b32 m0, s14
	ds_read_b128 v[164:167], v238 offset:16384
	ds_read_b128 v[168:171], v238 offset:17408
	ds_read_b128 v[172:175], v238 offset:18432
	ds_read_b128 v[176:179], v238 offset:19456
	ds_read_b128 v[180:183], v238 offset:20480
	ds_read_b128 v[184:187], v238 offset:21504
	ds_read_b128 v[188:191], v238 offset:22528
	ds_read_b128 v[192:195], v238 offset:23552
	global_load_lds_dwordx4 v[204:205], off
	s_add_i32 m0, s14, 0x2000
	s_add_u32 s14, s18, 0x160000
	v_lshl_add_u64 v[206:207], s[18:19], 0, v[198:199]
	s_addc_u32 s15, s19, 0
	s_add_i32 s44, s45, s22
	global_load_lds_dwordx4 v[206:207], off
	v_lshl_add_u64 v[208:209], s[14:15], 0, v[2:3]
	s_mov_b32 m0, s44
	v_lshl_add_u64 v[210:211], s[20:21], 0, v[196:197]
	global_load_lds_dwordx4 v[208:209], off
	v_lshl_add_u64 v[208:209], s[14:15], 0, v[198:199]
	s_add_i32 m0, s44, 0x2000
	s_nop 0
	global_load_lds_dwordx4 v[208:209], off
	v_lshl_add_u64 v[208:209], s[20:21], 0, v[0:1]
	s_mov_b32 m0, s23
	s_nop 0
	global_load_lds_dwordx4 v[208:209], off
	s_mov_b32 m0, s28
	s_nop 0
	global_load_lds_dwordx4 v[210:211], off
	s_waitcnt vmcnt(8)
	s_waitcnt lgkmcnt(0)
	s_barrier
	s_setprio 1
	s_waitcnt lgkmcnt(0)
	v_mfma_f32_16x16x32_bf16 v[64:67], v[132:135], v[164:167], v[64:67]
	v_mfma_f32_16x16x32_bf16 v[60:63], v[140:143], v[164:167], v[60:63]
	v_mfma_f32_16x16x32_bf16 v[52:55], v[132:135], v[172:175], v[52:55]
	v_mfma_f32_16x16x32_bf16 v[44:47], v[140:143], v[172:175], v[44:47]
	v_mfma_f32_16x16x32_bf16 v[36:39], v[132:135], v[180:183], v[36:39]
	v_mfma_f32_16x16x32_bf16 v[28:31], v[140:143], v[180:183], v[28:31]
	v_mfma_f32_16x16x32_bf16 v[20:23], v[132:135], v[188:191], v[20:23]
	v_mfma_f32_16x16x32_bf16 v[12:15], v[140:143], v[188:191], v[12:15]
	v_mfma_f32_16x16x32_bf16 v[64:67], v[136:139], v[168:171], v[64:67]
	v_mfma_f32_16x16x32_bf16 v[60:63], v[144:147], v[168:171], v[60:63]
	v_mfma_f32_16x16x32_bf16 v[52:55], v[136:139], v[176:179], v[52:55]
	v_mfma_f32_16x16x32_bf16 v[44:47], v[144:147], v[176:179], v[44:47]
	v_mfma_f32_16x16x32_bf16 v[36:39], v[136:139], v[184:187], v[36:39]
	v_mfma_f32_16x16x32_bf16 v[28:31], v[144:147], v[184:187], v[28:31]
	v_mfma_f32_16x16x32_bf16 v[20:23], v[136:139], v[192:195], v[20:23]
	v_mfma_f32_16x16x32_bf16 v[12:15], v[144:147], v[192:195], v[12:15]
	s_setprio 0
	s_setprio 1
	v_mfma_f32_16x16x32_bf16 v[56:59], v[148:151], v[164:167], v[56:59]
	v_mfma_f32_16x16x32_bf16 v[48:51], v[156:159], v[164:167], v[48:51]
	v_mfma_f32_16x16x32_bf16 v[40:43], v[148:151], v[172:175], v[40:43]
	v_mfma_f32_16x16x32_bf16 v[32:35], v[156:159], v[172:175], v[32:35]
	v_mfma_f32_16x16x32_bf16 v[24:27], v[148:151], v[180:183], v[24:27]
	v_mfma_f32_16x16x32_bf16 v[16:19], v[156:159], v[180:183], v[16:19]
	v_mfma_f32_16x16x32_bf16 v[8:11], v[148:151], v[188:191], v[8:11]
	v_mfma_f32_16x16x32_bf16 v[4:7], v[156:159], v[188:191], v[4:7]
	v_mfma_f32_16x16x32_bf16 v[56:59], v[152:155], v[168:171], v[56:59]
	v_mfma_f32_16x16x32_bf16 v[48:51], v[160:163], v[168:171], v[48:51]
	v_mfma_f32_16x16x32_bf16 v[40:43], v[152:155], v[176:179], v[40:43]
	v_mfma_f32_16x16x32_bf16 v[32:35], v[160:163], v[176:179], v[32:35]
	v_mfma_f32_16x16x32_bf16 v[24:27], v[152:155], v[184:187], v[24:27]
	v_mfma_f32_16x16x32_bf16 v[16:19], v[160:163], v[184:187], v[16:19]
	v_mfma_f32_16x16x32_bf16 v[8:11], v[152:155], v[192:195], v[8:11]
	v_mfma_f32_16x16x32_bf16 v[4:7], v[160:163], v[192:195], v[4:7]
	s_setprio 0
	s_barrier
	s_sleep 1
	s_add_i32 s44, 0, 0x18000
	s_add_i32 s45, 0, 0x1c000
	v_add_u32_e32 v144, s44, v236
	v_add_u32_e32 v160, s45, v236
	ds_read_b128 v[132:135], v144
	ds_read_b128 v[136:139], v144 offset:1024
	ds_read_b128 v[140:143], v144 offset:2048
	ds_read_b128 v[144:147], v144 offset:3072
	ds_read_b128 v[148:151], v160
	ds_read_b128 v[152:155], v160 offset:1024
	ds_read_b128 v[156:159], v160 offset:2048
	ds_read_b128 v[160:163], v160 offset:3072
	s_add_u32 s14, s20, 0x160000
	s_addc_u32 s15, s21, 0
	s_mov_b32 m0, s29
	v_lshl_add_u64 v[212:213], s[14:15], 0, v[0:1]
	ds_read_b128 v[164:167], v238 offset:32768
	ds_read_b128 v[168:171], v238 offset:33792
	ds_read_b128 v[172:175], v238 offset:34816
	ds_read_b128 v[176:179], v238 offset:35840
	ds_read_b128 v[180:183], v238 offset:36864
	ds_read_b128 v[184:187], v238 offset:37888
	ds_read_b128 v[188:191], v238 offset:38912
	ds_read_b128 v[192:195], v238 offset:39936
	global_load_lds_dwordx4 v[212:213], off
	v_lshl_add_u64 v[212:213], s[14:15], 0, v[196:197]
	s_mov_b32 m0, s30
	s_nop 0
	global_load_lds_dwordx4 v[212:213], off
	s_waitcnt vmcnt(8)
	s_waitcnt lgkmcnt(0)
	s_barrier
	s_setprio 1
	s_waitcnt lgkmcnt(0)
	v_mfma_f32_16x16x32_bf16 v[128:131], v[132:135], v[164:167], v[128:131]
	v_mfma_f32_16x16x32_bf16 v[124:127], v[140:143], v[164:167], v[124:127]
	v_mfma_f32_16x16x32_bf16 v[116:119], v[132:135], v[172:175], v[116:119]
	v_mfma_f32_16x16x32_bf16 v[108:111], v[140:143], v[172:175], v[108:111]
	v_mfma_f32_16x16x32_bf16 v[100:103], v[132:135], v[180:183], v[100:103]
	v_mfma_f32_16x16x32_bf16 v[92:95], v[140:143], v[180:183], v[92:95]
	v_mfma_f32_16x16x32_bf16 v[84:87], v[132:135], v[188:191], v[84:87]
	v_mfma_f32_16x16x32_bf16 v[76:79], v[140:143], v[188:191], v[76:79]
	v_mfma_f32_16x16x32_bf16 v[128:131], v[136:139], v[168:171], v[128:131]
	v_mfma_f32_16x16x32_bf16 v[124:127], v[144:147], v[168:171], v[124:127]
	v_mfma_f32_16x16x32_bf16 v[116:119], v[136:139], v[176:179], v[116:119]
	v_mfma_f32_16x16x32_bf16 v[108:111], v[144:147], v[176:179], v[108:111]
	v_mfma_f32_16x16x32_bf16 v[100:103], v[136:139], v[184:187], v[100:103]
	v_mfma_f32_16x16x32_bf16 v[92:95], v[144:147], v[184:187], v[92:95]
	v_mfma_f32_16x16x32_bf16 v[84:87], v[136:139], v[192:195], v[84:87]
	v_mfma_f32_16x16x32_bf16 v[76:79], v[144:147], v[192:195], v[76:79]
	s_setprio 0
	s_setprio 1
	v_mfma_f32_16x16x32_bf16 v[120:123], v[148:151], v[164:167], v[120:123]
	v_mfma_f32_16x16x32_bf16 v[112:115], v[156:159], v[164:167], v[112:115]
	v_mfma_f32_16x16x32_bf16 v[104:107], v[148:151], v[172:175], v[104:107]
	v_mfma_f32_16x16x32_bf16 v[96:99], v[156:159], v[172:175], v[96:99]
	v_mfma_f32_16x16x32_bf16 v[88:91], v[148:151], v[180:183], v[88:91]
	v_mfma_f32_16x16x32_bf16 v[80:83], v[156:159], v[180:183], v[80:83]
	v_mfma_f32_16x16x32_bf16 v[72:75], v[148:151], v[188:191], v[72:75]
	v_mfma_f32_16x16x32_bf16 v[68:71], v[156:159], v[188:191], v[68:71]
	v_mfma_f32_16x16x32_bf16 v[120:123], v[152:155], v[168:171], v[120:123]
	v_mfma_f32_16x16x32_bf16 v[112:115], v[160:163], v[168:171], v[112:115]
	v_mfma_f32_16x16x32_bf16 v[104:107], v[152:155], v[176:179], v[104:107]
	v_mfma_f32_16x16x32_bf16 v[96:99], v[160:163], v[176:179], v[96:99]
	v_mfma_f32_16x16x32_bf16 v[88:91], v[152:155], v[184:187], v[88:91]
	v_mfma_f32_16x16x32_bf16 v[80:83], v[160:163], v[184:187], v[80:83]
	v_mfma_f32_16x16x32_bf16 v[72:75], v[152:155], v[192:195], v[72:75]
	v_mfma_f32_16x16x32_bf16 v[68:71], v[160:163], v[192:195], v[68:71]
	s_setprio 0
	s_barrier
	s_sleep 1
	s_add_i32 s14, s44, s22
	v_lshl_add_u64 v[204:205], v[204:205], 0, s[66:67]
	s_mov_b32 m0, s14
	ds_read_b128 v[164:167], v238 offset:49152
	ds_read_b128 v[168:171], v238 offset:50176
	ds_read_b128 v[172:175], v238 offset:51200
	ds_read_b128 v[176:179], v238 offset:52224
	ds_read_b128 v[180:183], v238 offset:53248
	ds_read_b128 v[184:187], v238 offset:54272
	ds_read_b128 v[188:191], v238 offset:55296
	ds_read_b128 v[192:195], v238 offset:56320
	global_load_lds_dwordx4 v[204:205], off
	s_add_i32 m0, s14, 0x2000
	s_add_u32 s14, s18, 0x160080
	v_lshl_add_u64 v[204:205], v[206:207], 0, s[66:67]
	s_addc_u32 s15, s19, 0
	s_add_i32 s18, s45, s22
	global_load_lds_dwordx4 v[204:205], off
	v_lshl_add_u64 v[204:205], s[14:15], 0, v[2:3]
	s_mov_b32 m0, s18
	s_nop 0
	global_load_lds_dwordx4 v[204:205], off
	v_lshl_add_u64 v[204:205], s[14:15], 0, v[198:199]
	s_add_i32 m0, s18, 0x2000
	s_nop 0
	global_load_lds_dwordx4 v[204:205], off
	v_lshl_add_u64 v[204:205], v[208:209], 0, s[66:67]
	s_mov_b32 m0, s31
	s_nop 0
	global_load_lds_dwordx4 v[204:205], off
	v_lshl_add_u64 v[204:205], v[210:211], 0, s[66:67]
	s_mov_b32 m0, s34
	s_nop 0
	global_load_lds_dwordx4 v[204:205], off
	s_waitcnt vmcnt(8)
	s_waitcnt lgkmcnt(0)
	s_barrier
	s_setprio 1
	s_waitcnt lgkmcnt(0)
	v_mfma_f32_16x16x32_bf16 v[64:67], v[132:135], v[164:167], v[64:67]
	v_mfma_f32_16x16x32_bf16 v[60:63], v[140:143], v[164:167], v[60:63]
	v_mfma_f32_16x16x32_bf16 v[52:55], v[132:135], v[172:175], v[52:55]
	v_mfma_f32_16x16x32_bf16 v[44:47], v[140:143], v[172:175], v[44:47]
	v_mfma_f32_16x16x32_bf16 v[36:39], v[132:135], v[180:183], v[36:39]
	v_mfma_f32_16x16x32_bf16 v[28:31], v[140:143], v[180:183], v[28:31]
	v_mfma_f32_16x16x32_bf16 v[20:23], v[132:135], v[188:191], v[20:23]
	v_mfma_f32_16x16x32_bf16 v[12:15], v[140:143], v[188:191], v[12:15]
	v_mfma_f32_16x16x32_bf16 v[64:67], v[136:139], v[168:171], v[64:67]
	v_mfma_f32_16x16x32_bf16 v[60:63], v[144:147], v[168:171], v[60:63]
	v_mfma_f32_16x16x32_bf16 v[52:55], v[136:139], v[176:179], v[52:55]
	v_mfma_f32_16x16x32_bf16 v[44:47], v[144:147], v[176:179], v[44:47]
	v_mfma_f32_16x16x32_bf16 v[36:39], v[136:139], v[184:187], v[36:39]
	v_mfma_f32_16x16x32_bf16 v[28:31], v[144:147], v[184:187], v[28:31]
	v_mfma_f32_16x16x32_bf16 v[20:23], v[136:139], v[192:195], v[20:23]
	v_mfma_f32_16x16x32_bf16 v[12:15], v[144:147], v[192:195], v[12:15]
	s_setprio 0
	s_setprio 1
	v_mfma_f32_16x16x32_bf16 v[56:59], v[148:151], v[164:167], v[56:59]
	v_mfma_f32_16x16x32_bf16 v[48:51], v[156:159], v[164:167], v[48:51]
	v_mfma_f32_16x16x32_bf16 v[40:43], v[148:151], v[172:175], v[40:43]
	v_mfma_f32_16x16x32_bf16 v[32:35], v[156:159], v[172:175], v[32:35]
	v_mfma_f32_16x16x32_bf16 v[24:27], v[148:151], v[180:183], v[24:27]
	v_mfma_f32_16x16x32_bf16 v[16:19], v[156:159], v[180:183], v[16:19]
	v_mfma_f32_16x16x32_bf16 v[8:11], v[148:151], v[188:191], v[8:11]
	v_mfma_f32_16x16x32_bf16 v[4:7], v[156:159], v[188:191], v[4:7]
	v_mfma_f32_16x16x32_bf16 v[56:59], v[152:155], v[168:171], v[56:59]
	v_mfma_f32_16x16x32_bf16 v[48:51], v[160:163], v[168:171], v[48:51]
	v_mfma_f32_16x16x32_bf16 v[40:43], v[152:155], v[176:179], v[40:43]
	v_mfma_f32_16x16x32_bf16 v[32:35], v[160:163], v[176:179], v[32:35]
	v_mfma_f32_16x16x32_bf16 v[24:27], v[152:155], v[184:187], v[24:27]
	v_mfma_f32_16x16x32_bf16 v[16:19], v[160:163], v[184:187], v[16:19]
	v_mfma_f32_16x16x32_bf16 v[8:11], v[152:155], v[192:195], v[8:11]
	v_mfma_f32_16x16x32_bf16 v[4:7], v[160:163], v[192:195], v[4:7]
	s_setprio 0
	s_barrier
	s_add_i32 s43, s43, 2
	s_add_u32 s38, s38, 0x100
	s_addc_u32 s39, s39, 0
	s_cmpk_gt_u32 s43, 0x55
	s_mov_b64 s[14:15], s[16:17]
	s_cbranch_scc0 .LBB0_347
	s_and_b64 vcc, exec, s[6:7]
	s_cbranch_vccz .LBB0_350
	s_barrier

.LBB0_430:
	s_sleep 1
	s_add_u32 s30, s28, 0xfff80080
	s_addc_u32 s31, s29, -1
	s_add_i32 s70, 0, 0x10000
	s_cmp_eq_u32 s69, 28
	s_cselect_b32 s43, s5, s31
	s_cselect_b32 s42, s23, s30
	s_cselect_b32 s31, s21, s68
	s_cselect_b32 s30, s62, s63
	s_add_i32 s73, 0, 0x14000
	s_waitcnt lgkmcnt(0)
	v_add_u32_e32 v152, s70, v163
	v_add_u32_e32 v160, s73, v163
	ds_read_b128 v[132:135], v152
	ds_read_b128 v[136:139], v152 offset:1024
	ds_read_b128 v[148:151], v152 offset:2048
	ds_read_b128 v[152:155], v152 offset:3072
	ds_read_b128 v[156:159], v160
	ds_read_b128 v[170:173], v160 offset:1024
	ds_read_b128 v[174:177], v160 offset:2048
	ds_read_b128 v[178:181], v160 offset:3072
	v_lshl_add_u64 v[160:161], s[28:29], 0, v[144:145]
	s_add_i32 m0, s15, 0xc000
	ds_read_b128 v[182:185], v167
	ds_read_b128 v[186:189], v167 offset:1024
	ds_read_b128 v[190:193], v167 offset:2048
	ds_read_b128 v[194:197], v167 offset:3072
	ds_read_b128 v[198:201], v167 offset:4096
	ds_read_b128 v[208:211], v167 offset:5120
	ds_read_b128 v[212:215], v167 offset:6144
	ds_read_b128 v[216:219], v167 offset:7168
	global_load_lds_dwordx4 v[160:161], off
	v_lshl_add_u64 v[160:161], s[28:29], 0, v[146:147]
	s_add_i32 m0, s15, 0xe000
	s_nop 0
	global_load_lds_dwordx4 v[160:161], off
	s_waitcnt vmcnt(8)
	s_waitcnt lgkmcnt(0)
	s_barrier
	s_setprio 1
	s_waitcnt lgkmcnt(0)
	v_mfma_f32_16x16x32_bf16 v[128:131], v[132:135], v[182:185], v[128:131]
	v_mfma_f32_16x16x32_bf16 v[124:127], v[148:151], v[182:185], v[124:127]
	v_mfma_f32_16x16x32_bf16 v[120:123], v[132:135], v[190:193], v[120:123]
	v_mfma_f32_16x16x32_bf16 v[112:115], v[148:151], v[190:193], v[112:115]
	v_mfma_f32_16x16x32_bf16 v[104:107], v[132:135], v[198:201], v[104:107]
	v_mfma_f32_16x16x32_bf16 v[96:99], v[148:151], v[198:201], v[96:99]
	v_mfma_f32_16x16x32_bf16 v[88:91], v[132:135], v[212:215], v[88:91]
	v_mfma_f32_16x16x32_bf16 v[80:83], v[148:151], v[212:215], v[80:83]
	v_mfma_f32_16x16x32_bf16 v[128:131], v[136:139], v[186:189], v[128:131]
	v_mfma_f32_16x16x32_bf16 v[124:127], v[152:155], v[186:189], v[124:127]
	v_mfma_f32_16x16x32_bf16 v[120:123], v[136:139], v[194:197], v[120:123]
	v_mfma_f32_16x16x32_bf16 v[112:115], v[152:155], v[194:197], v[112:115]
	v_mfma_f32_16x16x32_bf16 v[104:107], v[136:139], v[208:211], v[104:107]
	v_mfma_f32_16x16x32_bf16 v[96:99], v[152:155], v[208:211], v[96:99]
	v_mfma_f32_16x16x32_bf16 v[88:91], v[136:139], v[216:219], v[88:91]
	v_mfma_f32_16x16x32_bf16 v[80:83], v[152:155], v[216:219], v[80:83]
	s_setprio 0
	s_setprio 1
	v_mfma_f32_16x16x32_bf16 v[116:119], v[156:159], v[182:185], v[116:119]
	v_mfma_f32_16x16x32_bf16 v[108:111], v[174:177], v[182:185], v[108:111]
	v_mfma_f32_16x16x32_bf16 v[100:103], v[156:159], v[190:193], v[100:103]
	v_mfma_f32_16x16x32_bf16 v[92:95], v[174:177], v[190:193], v[92:95]
	v_mfma_f32_16x16x32_bf16 v[84:87], v[156:159], v[198:201], v[84:87]
	v_mfma_f32_16x16x32_bf16 v[76:79], v[174:177], v[198:201], v[76:79]
	v_mfma_f32_16x16x32_bf16 v[72:75], v[156:159], v[212:215], v[72:75]
	v_mfma_f32_16x16x32_bf16 v[68:71], v[174:177], v[212:215], v[68:71]
	v_mfma_f32_16x16x32_bf16 v[116:119], v[170:173], v[186:189], v[116:119]
	v_mfma_f32_16x16x32_bf16 v[108:111], v[178:181], v[186:189], v[108:111]
	v_mfma_f32_16x16x32_bf16 v[100:103], v[170:173], v[194:197], v[100:103]
	v_mfma_f32_16x16x32_bf16 v[92:95], v[178:181], v[194:197], v[92:95]
	v_mfma_f32_16x16x32_bf16 v[84:87], v[170:173], v[208:211], v[84:87]
	v_mfma_f32_16x16x32_bf16 v[76:79], v[178:181], v[208:211], v[76:79]
	v_mfma_f32_16x16x32_bf16 v[72:75], v[170:173], v[216:219], v[72:75]
	v_mfma_f32_16x16x32_bf16 v[68:71], v[178:181], v[216:219], v[68:71]
	s_setprio 0
	s_barrier
	s_sleep 1
	s_add_i32 s70, s70, s0
	v_lshl_add_u64 v[160:161], s[30:31], 0, v[2:3]
	s_mov_b32 m0, s70
	ds_read_b128 v[182:185], v167 offset:16384
	ds_read_b128 v[186:189], v167 offset:17408
	ds_read_b128 v[190:193], v167 offset:18432
	ds_read_b128 v[194:197], v167 offset:19456
	ds_read_b128 v[198:201], v167 offset:20480
	ds_read_b128 v[208:211], v167 offset:21504
	ds_read_b128 v[212:215], v167 offset:22528
	ds_read_b128 v[216:219], v167 offset:23552
	global_load_lds_dwordx4 v[160:161], off
	s_add_i32 m0, s70, 0x2000
	s_add_u32 s70, s30, 0x80000
	v_lshl_add_u64 v[202:203], s[30:31], 0, v[142:143]
	s_addc_u32 s71, s31, 0
	s_add_i32 s73, s73, s0
	global_load_lds_dwordx4 v[202:203], off
	v_lshl_add_u64 v[204:205], s[70:71], 0, v[2:3]
	s_mov_b32 m0, s73
	v_lshl_add_u64 v[206:207], s[42:43], 0, v[140:141]
	global_load_lds_dwordx4 v[204:205], off
	v_lshl_add_u64 v[204:205], s[70:71], 0, v[142:143]
	s_add_i32 m0, s73, 0x2000
	s_nop 0
	global_load_lds_dwordx4 v[204:205], off
	v_lshl_add_u64 v[204:205], s[42:43], 0, v[0:1]
	s_mov_b32 m0, s15
	s_nop 0
	global_load_lds_dwordx4 v[204:205], off
	s_mov_b32 m0, s53
	s_nop 0
	global_load_lds_dwordx4 v[206:207], off
	s_waitcnt vmcnt(8)
	s_waitcnt lgkmcnt(0)
	s_barrier
	s_setprio 1
	s_waitcnt lgkmcnt(0)
	v_mfma_f32_16x16x32_bf16 v[64:67], v[132:135], v[182:185], v[64:67]
	v_mfma_f32_16x16x32_bf16 v[60:63], v[148:151], v[182:185], v[60:63]
	v_mfma_f32_16x16x32_bf16 v[56:59], v[132:135], v[190:193], v[56:59]
	v_mfma_f32_16x16x32_bf16 v[48:51], v[148:151], v[190:193], v[48:51]
	v_mfma_f32_16x16x32_bf16 v[40:43], v[132:135], v[198:201], v[40:43]
	v_mfma_f32_16x16x32_bf16 v[32:35], v[148:151], v[198:201], v[32:35]
	v_mfma_f32_16x16x32_bf16 v[24:27], v[132:135], v[212:215], v[24:27]
	v_mfma_f32_16x16x32_bf16 v[16:19], v[148:151], v[212:215], v[16:19]
	v_mfma_f32_16x16x32_bf16 v[64:67], v[136:139], v[186:189], v[64:67]
	v_mfma_f32_16x16x32_bf16 v[60:63], v[152:155], v[186:189], v[60:63]
	v_mfma_f32_16x16x32_bf16 v[56:59], v[136:139], v[194:197], v[56:59]
	v_mfma_f32_16x16x32_bf16 v[48:51], v[152:155], v[194:197], v[48:51]
	v_mfma_f32_16x16x32_bf16 v[40:43], v[136:139], v[208:211], v[40:43]
	v_mfma_f32_16x16x32_bf16 v[32:35], v[152:155], v[208:211], v[32:35]
	v_mfma_f32_16x16x32_bf16 v[24:27], v[136:139], v[216:219], v[24:27]
	v_mfma_f32_16x16x32_bf16 v[16:19], v[152:155], v[216:219], v[16:19]
	s_setprio 0
	s_setprio 1
	v_mfma_f32_16x16x32_bf16 v[52:55], v[156:159], v[182:185], v[52:55]
	v_mfma_f32_16x16x32_bf16 v[44:47], v[174:177], v[182:185], v[44:47]
	v_mfma_f32_16x16x32_bf16 v[36:39], v[156:159], v[190:193], v[36:39]
	v_mfma_f32_16x16x32_bf16 v[28:31], v[174:177], v[190:193], v[28:31]
	v_mfma_f32_16x16x32_bf16 v[20:23], v[156:159], v[198:201], v[20:23]
	v_mfma_f32_16x16x32_bf16 v[12:15], v[174:177], v[198:201], v[12:15]
	v_mfma_f32_16x16x32_bf16 v[8:11], v[156:159], v[212:215], v[8:11]
	v_mfma_f32_16x16x32_bf16 v[4:7], v[174:177], v[212:215], v[4:7]
	v_mfma_f32_16x16x32_bf16 v[52:55], v[170:173], v[186:189], v[52:55]
	v_mfma_f32_16x16x32_bf16 v[44:47], v[178:181], v[186:189], v[44:47]
	v_mfma_f32_16x16x32_bf16 v[36:39], v[170:173], v[194:197], v[36:39]
	v_mfma_f32_16x16x32_bf16 v[28:31], v[178:181], v[194:197], v[28:31]
	v_mfma_f32_16x16x32_bf16 v[20:23], v[170:173], v[208:211], v[20:23]
	v_mfma_f32_16x16x32_bf16 v[12:15], v[178:181], v[208:211], v[12:15]
	v_mfma_f32_16x16x32_bf16 v[8:11], v[170:173], v[216:219], v[8:11]
	v_mfma_f32_16x16x32_bf16 v[4:7], v[178:181], v[216:219], v[4:7]
	s_setprio 0
	s_barrier
	s_sleep 1
	s_add_i32 s70, 0, 0x18000
	s_add_i32 s71, 0, 0x1c000
	v_add_u32_e32 v152, s70, v163
	v_add_u32_e32 v178, s71, v163
	ds_read_b128 v[132:135], v152
	ds_read_b128 v[136:139], v152 offset:1024
	ds_read_b128 v[148:151], v152 offset:2048
	ds_read_b128 v[152:155], v152 offset:3072
	ds_read_b128 v[156:159], v178
	ds_read_b128 v[170:173], v178 offset:1024
	ds_read_b128 v[174:177], v178 offset:2048
	ds_read_b128 v[178:181], v178 offset:3072
	s_add_u32 s42, s42, 0x80000
	s_addc_u32 s43, s43, 0
	s_mov_b32 m0, s54
	v_lshl_add_u64 v[220:221], s[42:43], 0, v[0:1]
	ds_read_b128 v[182:185], v167 offset:32768
	ds_read_b128 v[186:189], v167 offset:33792
	ds_read_b128 v[190:193], v167 offset:34816
	ds_read_b128 v[194:197], v167 offset:35840
	ds_read_b128 v[198:201], v167 offset:36864
	ds_read_b128 v[208:211], v167 offset:37888
	ds_read_b128 v[212:215], v167 offset:38912
	ds_read_b128 v[216:219], v167 offset:39936
	global_load_lds_dwordx4 v[220:221], off
	v_lshl_add_u64 v[220:221], s[42:43], 0, v[140:141]
	s_mov_b32 m0, s55
	s_nop 0
	global_load_lds_dwordx4 v[220:221], off
	s_waitcnt vmcnt(8)
	s_waitcnt lgkmcnt(0)
	s_barrier
	s_setprio 1
	s_waitcnt lgkmcnt(0)
	v_mfma_f32_16x16x32_bf16 v[128:131], v[132:135], v[182:185], v[128:131]
	v_mfma_f32_16x16x32_bf16 v[124:127], v[148:151], v[182:185], v[124:127]
	v_mfma_f32_16x16x32_bf16 v[120:123], v[132:135], v[190:193], v[120:123]
	v_mfma_f32_16x16x32_bf16 v[112:115], v[148:151], v[190:193], v[112:115]
	v_mfma_f32_16x16x32_bf16 v[104:107], v[132:135], v[198:201], v[104:107]
	v_mfma_f32_16x16x32_bf16 v[96:99], v[148:151], v[198:201], v[96:99]
	v_mfma_f32_16x16x32_bf16 v[88:91], v[132:135], v[212:215], v[88:91]
	v_mfma_f32_16x16x32_bf16 v[80:83], v[148:151], v[212:215], v[80:83]
	v_mfma_f32_16x16x32_bf16 v[128:131], v[136:139], v[186:189], v[128:131]
	v_mfma_f32_16x16x32_bf16 v[124:127], v[152:155], v[186:189], v[124:127]
	v_mfma_f32_16x16x32_bf16 v[120:123], v[136:139], v[194:197], v[120:123]
	v_mfma_f32_16x16x32_bf16 v[112:115], v[152:155], v[194:197], v[112:115]
	v_mfma_f32_16x16x32_bf16 v[104:107], v[136:139], v[208:211], v[104:107]
	v_mfma_f32_16x16x32_bf16 v[96:99], v[152:155], v[208:211], v[96:99]
	v_mfma_f32_16x16x32_bf16 v[88:91], v[136:139], v[216:219], v[88:91]
	v_mfma_f32_16x16x32_bf16 v[80:83], v[152:155], v[216:219], v[80:83]
	s_setprio 0
	s_setprio 1
	v_mfma_f32_16x16x32_bf16 v[116:119], v[156:159], v[182:185], v[116:119]
	v_mfma_f32_16x16x32_bf16 v[108:111], v[174:177], v[182:185], v[108:111]
	v_mfma_f32_16x16x32_bf16 v[100:103], v[156:159], v[190:193], v[100:103]
	v_mfma_f32_16x16x32_bf16 v[92:95], v[174:177], v[190:193], v[92:95]
	v_mfma_f32_16x16x32_bf16 v[84:87], v[156:159], v[198:201], v[84:87]
	v_mfma_f32_16x16x32_bf16 v[76:79], v[174:177], v[198:201], v[76:79]
	v_mfma_f32_16x16x32_bf16 v[72:75], v[156:159], v[212:215], v[72:75]
	v_mfma_f32_16x16x32_bf16 v[68:71], v[174:177], v[212:215], v[68:71]
	v_mfma_f32_16x16x32_bf16 v[116:119], v[170:173], v[186:189], v[116:119]
	v_mfma_f32_16x16x32_bf16 v[108:111], v[178:181], v[186:189], v[108:111]
	v_mfma_f32_16x16x32_bf16 v[100:103], v[170:173], v[194:197], v[100:103]
	v_mfma_f32_16x16x32_bf16 v[92:95], v[178:181], v[194:197], v[92:95]
	v_mfma_f32_16x16x32_bf16 v[84:87], v[170:173], v[208:211], v[84:87]
	v_mfma_f32_16x16x32_bf16 v[76:79], v[178:181], v[208:211], v[76:79]
	v_mfma_f32_16x16x32_bf16 v[72:75], v[170:173], v[216:219], v[72:75]
	v_mfma_f32_16x16x32_bf16 v[68:71], v[178:181], v[216:219], v[68:71]
	s_setprio 0
	s_barrier
	s_sleep 1
	s_add_i32 s42, s70, s0
	v_lshl_add_u64 v[160:161], v[160:161], 0, s[66:67]
	s_mov_b32 m0, s42
	ds_read_b128 v[182:185], v167 offset:49152
	ds_read_b128 v[186:189], v167 offset:50176
	ds_read_b128 v[190:193], v167 offset:51200
	ds_read_b128 v[194:197], v167 offset:52224
	ds_read_b128 v[198:201], v167 offset:53248
	ds_read_b128 v[208:211], v167 offset:54272
	ds_read_b128 v[212:215], v167 offset:55296
	ds_read_b128 v[216:219], v167 offset:56320
	global_load_lds_dwordx4 v[160:161], off
	s_add_i32 m0, s42, 0x2000
	s_add_u32 s30, s30, 0x80080
	v_lshl_add_u64 v[160:161], v[202:203], 0, s[66:67]
	s_addc_u32 s31, s31, 0
	s_add_i32 s42, s71, s0
	global_load_lds_dwordx4 v[160:161], off
	v_lshl_add_u64 v[160:161], s[30:31], 0, v[2:3]
	s_mov_b32 m0, s42
	s_nop 0
	global_load_lds_dwordx4 v[160:161], off
	v_lshl_add_u64 v[160:161], s[30:31], 0, v[142:143]
	s_add_i32 m0, s42, 0x2000
	s_nop 0
	global_load_lds_dwordx4 v[160:161], off
	v_lshl_add_u64 v[160:161], v[204:205], 0, s[66:67]
	s_mov_b32 m0, s60
	s_nop 0
	global_load_lds_dwordx4 v[160:161], off
	v_lshl_add_u64 v[160:161], v[206:207], 0, s[66:67]
	s_mov_b32 m0, s64
	s_nop 0
	global_load_lds_dwordx4 v[160:161], off
	s_waitcnt vmcnt(8)
	s_waitcnt lgkmcnt(0)
	s_barrier
	s_setprio 1
	s_waitcnt lgkmcnt(0)
	v_mfma_f32_16x16x32_bf16 v[64:67], v[132:135], v[182:185], v[64:67]
	v_mfma_f32_16x16x32_bf16 v[60:63], v[148:151], v[182:185], v[60:63]
	v_mfma_f32_16x16x32_bf16 v[56:59], v[132:135], v[190:193], v[56:59]
	v_mfma_f32_16x16x32_bf16 v[48:51], v[148:151], v[190:193], v[48:51]
	v_mfma_f32_16x16x32_bf16 v[40:43], v[132:135], v[198:201], v[40:43]
	v_mfma_f32_16x16x32_bf16 v[32:35], v[148:151], v[198:201], v[32:35]
	v_mfma_f32_16x16x32_bf16 v[24:27], v[132:135], v[212:215], v[24:27]
	v_mfma_f32_16x16x32_bf16 v[16:19], v[148:151], v[212:215], v[16:19]
	v_mfma_f32_16x16x32_bf16 v[64:67], v[136:139], v[186:189], v[64:67]
	v_mfma_f32_16x16x32_bf16 v[60:63], v[152:155], v[186:189], v[60:63]
	v_mfma_f32_16x16x32_bf16 v[56:59], v[136:139], v[194:197], v[56:59]
	v_mfma_f32_16x16x32_bf16 v[48:51], v[152:155], v[194:197], v[48:51]
	v_mfma_f32_16x16x32_bf16 v[40:43], v[136:139], v[208:211], v[40:43]
	v_mfma_f32_16x16x32_bf16 v[32:35], v[152:155], v[208:211], v[32:35]
	v_mfma_f32_16x16x32_bf16 v[24:27], v[136:139], v[216:219], v[24:27]
	v_mfma_f32_16x16x32_bf16 v[16:19], v[152:155], v[216:219], v[16:19]
	s_setprio 0
	s_setprio 1
	v_mfma_f32_16x16x32_bf16 v[52:55], v[156:159], v[182:185], v[52:55]
	v_mfma_f32_16x16x32_bf16 v[44:47], v[174:177], v[182:185], v[44:47]
	v_mfma_f32_16x16x32_bf16 v[36:39], v[156:159], v[190:193], v[36:39]
	v_mfma_f32_16x16x32_bf16 v[28:31], v[174:177], v[190:193], v[28:31]
	v_mfma_f32_16x16x32_bf16 v[20:23], v[156:159], v[198:201], v[20:23]
	v_mfma_f32_16x16x32_bf16 v[12:15], v[174:177], v[198:201], v[12:15]
	v_mfma_f32_16x16x32_bf16 v[8:11], v[156:159], v[212:215], v[8:11]
	v_mfma_f32_16x16x32_bf16 v[4:7], v[174:177], v[212:215], v[4:7]
	v_mfma_f32_16x16x32_bf16 v[52:55], v[170:173], v[186:189], v[52:55]
	v_mfma_f32_16x16x32_bf16 v[44:47], v[178:181], v[186:189], v[44:47]
	v_mfma_f32_16x16x32_bf16 v[36:39], v[170:173], v[194:197], v[36:39]
	v_mfma_f32_16x16x32_bf16 v[28:31], v[178:181], v[194:197], v[28:31]
	v_mfma_f32_16x16x32_bf16 v[20:23], v[170:173], v[208:211], v[20:23]
	v_mfma_f32_16x16x32_bf16 v[12:15], v[178:181], v[208:211], v[12:15]
	v_mfma_f32_16x16x32_bf16 v[8:11], v[170:173], v[216:219], v[8:11]
	v_mfma_f32_16x16x32_bf16 v[4:7], v[178:181], v[216:219], v[4:7]
	s_setprio 0
	s_barrier
	s_add_i32 s69, s69, 2
	s_add_u32 s28, s28, 0x100
	s_addc_u32 s29, s29, 0
	s_add_u32 s63, s63, 0x100
	s_addc_u32 s68, s68, 0
	s_cmp_gt_u32 s69, 29
	s_cbranch_scc0 .LBB0_430
	s_and_b64 vcc, exec, s[8:9]
	s_cbranch_vccz .LBB0_433
	s_barrier

.LBB0_495:
	s_sleep 1
	s_add_u32 s22, s20, 0xfff80080
	s_addc_u32 s23, s21, -1
	s_add_i32 s48, 0, 0x10000
	s_cmp_eq_u32 s47, 28
	s_cselect_b32 s25, s15, s23
	s_cselect_b32 s24, s43, s22
	s_cselect_b32 s23, s11, s46
	s_cselect_b32 s22, s44, s45
	s_add_i32 s50, 0, 0x14000
	s_waitcnt lgkmcnt(0)
	v_add_u32_e32 v152, s48, v137
	v_add_u32_e32 v168, s50, v137
	ds_read_b128 v[140:143], v152
	ds_read_b128 v[144:147], v152 offset:1024
	ds_read_b128 v[148:151], v152 offset:2048
	ds_read_b128 v[152:155], v152 offset:3072
	ds_read_b128 v[156:159], v168
	ds_read_b128 v[160:163], v168 offset:1024
	ds_read_b128 v[164:167], v168 offset:2048
	ds_read_b128 v[168:171], v168 offset:3072
	v_lshl_add_u64 v[204:205], s[20:21], 0, v[132:133]
	s_add_i32 m0, s31, 0xc000
	ds_read_b128 v[172:175], v139
	ds_read_b128 v[176:179], v139 offset:1024
	ds_read_b128 v[180:183], v139 offset:2048
	ds_read_b128 v[184:187], v139 offset:3072
	ds_read_b128 v[188:191], v139 offset:4096
	ds_read_b128 v[192:195], v139 offset:5120
	ds_read_b128 v[196:199], v139 offset:6144
	ds_read_b128 v[200:203], v139 offset:7168
	global_load_lds_dwordx4 v[204:205], off
	v_lshl_add_u64 v[204:205], s[20:21], 0, v[134:135]
	s_add_i32 m0, s31, 0xe000
	s_nop 0
	global_load_lds_dwordx4 v[204:205], off
	s_waitcnt vmcnt(8)
	s_waitcnt lgkmcnt(0)
	s_barrier
	s_setprio 1
	s_waitcnt lgkmcnt(0)
	v_mfma_f32_16x16x32_bf16 v[128:131], v[140:143], v[172:175], v[128:131]
	v_mfma_f32_16x16x32_bf16 v[124:127], v[148:151], v[172:175], v[124:127]
	v_mfma_f32_16x16x32_bf16 v[120:123], v[140:143], v[180:183], v[120:123]
	v_mfma_f32_16x16x32_bf16 v[116:119], v[148:151], v[180:183], v[116:119]
	v_mfma_f32_16x16x32_bf16 v[108:111], v[140:143], v[188:191], v[108:111]
	v_mfma_f32_16x16x32_bf16 v[100:103], v[148:151], v[188:191], v[100:103]
	v_mfma_f32_16x16x32_bf16 v[92:95], v[140:143], v[196:199], v[92:95]
	v_mfma_f32_16x16x32_bf16 v[84:87], v[148:151], v[196:199], v[84:87]
	v_mfma_f32_16x16x32_bf16 v[128:131], v[144:147], v[176:179], v[128:131]
	v_mfma_f32_16x16x32_bf16 v[124:127], v[152:155], v[176:179], v[124:127]
	v_mfma_f32_16x16x32_bf16 v[120:123], v[144:147], v[184:187], v[120:123]
	v_mfma_f32_16x16x32_bf16 v[116:119], v[152:155], v[184:187], v[116:119]
	v_mfma_f32_16x16x32_bf16 v[108:111], v[144:147], v[192:195], v[108:111]
	v_mfma_f32_16x16x32_bf16 v[100:103], v[152:155], v[192:195], v[100:103]
	v_mfma_f32_16x16x32_bf16 v[92:95], v[144:147], v[200:203], v[92:95]
	v_mfma_f32_16x16x32_bf16 v[84:87], v[152:155], v[200:203], v[84:87]
	s_setprio 0
	s_setprio 1
	v_mfma_f32_16x16x32_bf16 v[112:115], v[156:159], v[172:175], v[112:115]
	v_mfma_f32_16x16x32_bf16 v[104:107], v[164:167], v[172:175], v[104:107]
	v_mfma_f32_16x16x32_bf16 v[96:99], v[156:159], v[180:183], v[96:99]
	v_mfma_f32_16x16x32_bf16 v[88:91], v[164:167], v[180:183], v[88:91]
	v_mfma_f32_16x16x32_bf16 v[80:83], v[156:159], v[188:191], v[80:83]
	v_mfma_f32_16x16x32_bf16 v[76:79], v[164:167], v[188:191], v[76:79]
	v_mfma_f32_16x16x32_bf16 v[72:75], v[156:159], v[196:199], v[72:75]
	v_mfma_f32_16x16x32_bf16 v[68:71], v[164:167], v[196:199], v[68:71]
	v_mfma_f32_16x16x32_bf16 v[112:115], v[160:163], v[176:179], v[112:115]
	v_mfma_f32_16x16x32_bf16 v[104:107], v[168:171], v[176:179], v[104:107]
	v_mfma_f32_16x16x32_bf16 v[96:99], v[160:163], v[184:187], v[96:99]
	v_mfma_f32_16x16x32_bf16 v[88:91], v[168:171], v[184:187], v[88:91]
	v_mfma_f32_16x16x32_bf16 v[80:83], v[160:163], v[192:195], v[80:83]
	v_mfma_f32_16x16x32_bf16 v[76:79], v[168:171], v[192:195], v[76:79]
	v_mfma_f32_16x16x32_bf16 v[72:75], v[160:163], v[200:203], v[72:75]
	v_mfma_f32_16x16x32_bf16 v[68:71], v[168:171], v[200:203], v[68:71]
	s_setprio 0
	s_barrier
	s_sleep 1
	s_add_i32 s48, s48, s0
	v_lshl_add_u64 v[204:205], s[22:23], 0, v[2:3]
	s_mov_b32 m0, s48
	ds_read_b128 v[172:175], v139 offset:16384
	ds_read_b128 v[176:179], v139 offset:17408
	ds_read_b128 v[180:183], v139 offset:18432
	ds_read_b128 v[184:187], v139 offset:19456
	ds_read_b128 v[188:191], v139 offset:20480
	ds_read_b128 v[192:195], v139 offset:21504
	ds_read_b128 v[196:199], v139 offset:22528
	ds_read_b128 v[200:203], v139 offset:23552
	global_load_lds_dwordx4 v[204:205], off
	s_add_i32 m0, s48, 0x2000
	s_add_u32 s48, s22, 0x80000
	v_lshl_add_u64 v[206:207], s[22:23], 0, v[0:1]
	s_addc_u32 s49, s23, 0
	s_add_i32 s50, s50, s0
	global_load_lds_dwordx4 v[206:207], off
	v_lshl_add_u64 v[208:209], s[48:49], 0, v[2:3]
	s_mov_b32 m0, s50
	v_lshl_add_u64 v[210:211], s[24:25], 0, v[0:1]
	global_load_lds_dwordx4 v[208:209], off
	v_lshl_add_u64 v[208:209], s[48:49], 0, v[0:1]
	s_add_i32 m0, s50, 0x2000
	s_nop 0
	global_load_lds_dwordx4 v[208:209], off
	v_lshl_add_u64 v[208:209], s[24:25], 0, v[2:3]
	s_mov_b32 m0, s31
	s_nop 0
	global_load_lds_dwordx4 v[208:209], off
	s_mov_b32 m0, s40
	s_nop 0
	global_load_lds_dwordx4 v[210:211], off
	s_waitcnt vmcnt(8)
	s_waitcnt lgkmcnt(0)
	s_barrier
	s_setprio 1
	s_waitcnt lgkmcnt(0)
	v_mfma_f32_16x16x32_bf16 v[64:67], v[140:143], v[172:175], v[64:67]
	v_mfma_f32_16x16x32_bf16 v[60:63], v[148:151], v[172:175], v[60:63]
	v_mfma_f32_16x16x32_bf16 v[56:59], v[140:143], v[180:183], v[56:59]
	v_mfma_f32_16x16x32_bf16 v[52:55], v[148:151], v[180:183], v[52:55]
	v_mfma_f32_16x16x32_bf16 v[40:43], v[140:143], v[188:191], v[40:43]
	v_mfma_f32_16x16x32_bf16 v[36:39], v[148:151], v[188:191], v[36:39]
	v_mfma_f32_16x16x32_bf16 v[24:27], v[140:143], v[196:199], v[24:27]
	v_mfma_f32_16x16x32_bf16 v[20:23], v[148:151], v[196:199], v[20:23]
	v_mfma_f32_16x16x32_bf16 v[64:67], v[144:147], v[176:179], v[64:67]
	v_mfma_f32_16x16x32_bf16 v[60:63], v[152:155], v[176:179], v[60:63]
	v_mfma_f32_16x16x32_bf16 v[56:59], v[144:147], v[184:187], v[56:59]
	v_mfma_f32_16x16x32_bf16 v[52:55], v[152:155], v[184:187], v[52:55]
	v_mfma_f32_16x16x32_bf16 v[40:43], v[144:147], v[192:195], v[40:43]
	v_mfma_f32_16x16x32_bf16 v[36:39], v[152:155], v[192:195], v[36:39]
	v_mfma_f32_16x16x32_bf16 v[24:27], v[144:147], v[200:203], v[24:27]
	v_mfma_f32_16x16x32_bf16 v[20:23], v[152:155], v[200:203], v[20:23]
	s_setprio 0
	s_setprio 1
	v_mfma_f32_16x16x32_bf16 v[48:51], v[156:159], v[172:175], v[48:51]
	v_mfma_f32_16x16x32_bf16 v[44:47], v[164:167], v[172:175], v[44:47]
	v_mfma_f32_16x16x32_bf16 v[32:35], v[156:159], v[180:183], v[32:35]
	v_mfma_f32_16x16x32_bf16 v[28:31], v[164:167], v[180:183], v[28:31]
	v_mfma_f32_16x16x32_bf16 v[16:19], v[156:159], v[188:191], v[16:19]
	v_mfma_f32_16x16x32_bf16 v[12:15], v[164:167], v[188:191], v[12:15]
	v_mfma_f32_16x16x32_bf16 v[8:11], v[156:159], v[196:199], v[8:11]
	v_mfma_f32_16x16x32_bf16 v[4:7], v[164:167], v[196:199], v[4:7]
	v_mfma_f32_16x16x32_bf16 v[48:51], v[160:163], v[176:179], v[48:51]
	v_mfma_f32_16x16x32_bf16 v[44:47], v[168:171], v[176:179], v[44:47]
	v_mfma_f32_16x16x32_bf16 v[32:35], v[160:163], v[184:187], v[32:35]
	v_mfma_f32_16x16x32_bf16 v[28:31], v[168:171], v[184:187], v[28:31]
	v_mfma_f32_16x16x32_bf16 v[16:19], v[160:163], v[192:195], v[16:19]
	v_mfma_f32_16x16x32_bf16 v[12:15], v[168:171], v[192:195], v[12:15]
	v_mfma_f32_16x16x32_bf16 v[8:11], v[160:163], v[200:203], v[8:11]
	v_mfma_f32_16x16x32_bf16 v[4:7], v[168:171], v[200:203], v[4:7]
	s_setprio 0
	s_barrier
	s_sleep 1
	s_add_i32 s48, 0, 0x18000
	s_add_i32 s49, 0, 0x1c000
	v_add_u32_e32 v152, s48, v137
	v_add_u32_e32 v168, s49, v137
	ds_read_b128 v[140:143], v152
	ds_read_b128 v[144:147], v152 offset:1024
	ds_read_b128 v[148:151], v152 offset:2048
	ds_read_b128 v[152:155], v152 offset:3072
	ds_read_b128 v[156:159], v168
	ds_read_b128 v[160:163], v168 offset:1024
	ds_read_b128 v[164:167], v168 offset:2048
	ds_read_b128 v[168:171], v168 offset:3072
	s_add_u32 s24, s24, 0x80000
	s_addc_u32 s25, s25, 0
	s_mov_b32 m0, s41
	v_lshl_add_u64 v[212:213], s[24:25], 0, v[2:3]
	ds_read_b128 v[172:175], v139 offset:32768
	ds_read_b128 v[176:179], v139 offset:33792
	ds_read_b128 v[180:183], v139 offset:34816
	ds_read_b128 v[184:187], v139 offset:35840
	ds_read_b128 v[188:191], v139 offset:36864
	ds_read_b128 v[192:195], v139 offset:37888
	ds_read_b128 v[196:199], v139 offset:38912
	ds_read_b128 v[200:203], v139 offset:39936
	global_load_lds_dwordx4 v[212:213], off
	v_lshl_add_u64 v[212:213], s[24:25], 0, v[0:1]
	s_mov_b32 m0, s42
	s_nop 0
	global_load_lds_dwordx4 v[212:213], off
	s_waitcnt vmcnt(8)
	s_waitcnt lgkmcnt(0)
	s_barrier
	s_setprio 1
	s_waitcnt lgkmcnt(0)
	v_mfma_f32_16x16x32_bf16 v[128:131], v[140:143], v[172:175], v[128:131]
	v_mfma_f32_16x16x32_bf16 v[124:127], v[148:151], v[172:175], v[124:127]
	v_mfma_f32_16x16x32_bf16 v[120:123], v[140:143], v[180:183], v[120:123]
	v_mfma_f32_16x16x32_bf16 v[116:119], v[148:151], v[180:183], v[116:119]
	v_mfma_f32_16x16x32_bf16 v[108:111], v[140:143], v[188:191], v[108:111]
	v_mfma_f32_16x16x32_bf16 v[100:103], v[148:151], v[188:191], v[100:103]
	v_mfma_f32_16x16x32_bf16 v[92:95], v[140:143], v[196:199], v[92:95]
	v_mfma_f32_16x16x32_bf16 v[84:87], v[148:151], v[196:199], v[84:87]
	v_mfma_f32_16x16x32_bf16 v[128:131], v[144:147], v[176:179], v[128:131]
	v_mfma_f32_16x16x32_bf16 v[124:127], v[152:155], v[176:179], v[124:127]
	v_mfma_f32_16x16x32_bf16 v[120:123], v[144:147], v[184:187], v[120:123]
	v_mfma_f32_16x16x32_bf16 v[116:119], v[152:155], v[184:187], v[116:119]
	v_mfma_f32_16x16x32_bf16 v[108:111], v[144:147], v[192:195], v[108:111]
	v_mfma_f32_16x16x32_bf16 v[100:103], v[152:155], v[192:195], v[100:103]
	v_mfma_f32_16x16x32_bf16 v[92:95], v[144:147], v[200:203], v[92:95]
	v_mfma_f32_16x16x32_bf16 v[84:87], v[152:155], v[200:203], v[84:87]
	s_setprio 0
	s_setprio 1
	v_mfma_f32_16x16x32_bf16 v[112:115], v[156:159], v[172:175], v[112:115]
	v_mfma_f32_16x16x32_bf16 v[104:107], v[164:167], v[172:175], v[104:107]
	v_mfma_f32_16x16x32_bf16 v[96:99], v[156:159], v[180:183], v[96:99]
	v_mfma_f32_16x16x32_bf16 v[88:91], v[164:167], v[180:183], v[88:91]
	v_mfma_f32_16x16x32_bf16 v[80:83], v[156:159], v[188:191], v[80:83]
	v_mfma_f32_16x16x32_bf16 v[76:79], v[164:167], v[188:191], v[76:79]
	v_mfma_f32_16x16x32_bf16 v[72:75], v[156:159], v[196:199], v[72:75]
	v_mfma_f32_16x16x32_bf16 v[68:71], v[164:167], v[196:199], v[68:71]
	v_mfma_f32_16x16x32_bf16 v[112:115], v[160:163], v[176:179], v[112:115]
	v_mfma_f32_16x16x32_bf16 v[104:107], v[168:171], v[176:179], v[104:107]
	v_mfma_f32_16x16x32_bf16 v[96:99], v[160:163], v[184:187], v[96:99]
	v_mfma_f32_16x16x32_bf16 v[88:91], v[168:171], v[184:187], v[88:91]
	v_mfma_f32_16x16x32_bf16 v[80:83], v[160:163], v[192:195], v[80:83]
	v_mfma_f32_16x16x32_bf16 v[76:79], v[168:171], v[192:195], v[76:79]
	v_mfma_f32_16x16x32_bf16 v[72:75], v[160:163], v[200:203], v[72:75]
	v_mfma_f32_16x16x32_bf16 v[68:71], v[168:171], v[200:203], v[68:71]
	s_setprio 0
	s_barrier
	s_sleep 1
	s_add_i32 s24, s48, s0
	v_lshl_add_u64 v[204:205], v[204:205], 0, s[66:67]
	s_mov_b32 m0, s24
	ds_read_b128 v[172:175], v139 offset:49152
	ds_read_b128 v[176:179], v139 offset:50176
	ds_read_b128 v[180:183], v139 offset:51200
	ds_read_b128 v[184:187], v139 offset:52224
	ds_read_b128 v[188:191], v139 offset:53248
	ds_read_b128 v[192:195], v139 offset:54272
	ds_read_b128 v[196:199], v139 offset:55296
	ds_read_b128 v[200:203], v139 offset:56320
	global_load_lds_dwordx4 v[204:205], off
	s_add_i32 m0, s24, 0x2000
	s_add_u32 s22, s22, 0x80080
	v_lshl_add_u64 v[204:205], v[206:207], 0, s[66:67]
	s_addc_u32 s23, s23, 0
	s_add_i32 s24, s49, s0
	global_load_lds_dwordx4 v[204:205], off
	v_lshl_add_u64 v[204:205], s[22:23], 0, v[2:3]
	s_mov_b32 m0, s24
	s_nop 0
	global_load_lds_dwordx4 v[204:205], off
	v_lshl_add_u64 v[204:205], s[22:23], 0, v[0:1]
	s_add_i32 m0, s24, 0x2000
	s_nop 0
	global_load_lds_dwordx4 v[204:205], off
	v_lshl_add_u64 v[204:205], v[208:209], 0, s[66:67]
	s_mov_b32 m0, s1
	s_nop 0
	global_load_lds_dwordx4 v[204:205], off
	v_lshl_add_u64 v[204:205], v[210:211], 0, s[66:67]
	s_mov_b32 m0, s34
	s_nop 0
	global_load_lds_dwordx4 v[204:205], off
	s_waitcnt vmcnt(8)
	s_waitcnt lgkmcnt(0)
	s_barrier
	s_setprio 1
	s_waitcnt lgkmcnt(0)
	v_mfma_f32_16x16x32_bf16 v[64:67], v[140:143], v[172:175], v[64:67]
	v_mfma_f32_16x16x32_bf16 v[60:63], v[148:151], v[172:175], v[60:63]
	v_mfma_f32_16x16x32_bf16 v[56:59], v[140:143], v[180:183], v[56:59]
	v_mfma_f32_16x16x32_bf16 v[52:55], v[148:151], v[180:183], v[52:55]
	v_mfma_f32_16x16x32_bf16 v[40:43], v[140:143], v[188:191], v[40:43]
	v_mfma_f32_16x16x32_bf16 v[36:39], v[148:151], v[188:191], v[36:39]
	v_mfma_f32_16x16x32_bf16 v[24:27], v[140:143], v[196:199], v[24:27]
	v_mfma_f32_16x16x32_bf16 v[20:23], v[148:151], v[196:199], v[20:23]
	v_mfma_f32_16x16x32_bf16 v[64:67], v[144:147], v[176:179], v[64:67]
	v_mfma_f32_16x16x32_bf16 v[60:63], v[152:155], v[176:179], v[60:63]
	v_mfma_f32_16x16x32_bf16 v[56:59], v[144:147], v[184:187], v[56:59]
	v_mfma_f32_16x16x32_bf16 v[52:55], v[152:155], v[184:187], v[52:55]
	v_mfma_f32_16x16x32_bf16 v[40:43], v[144:147], v[192:195], v[40:43]
	v_mfma_f32_16x16x32_bf16 v[36:39], v[152:155], v[192:195], v[36:39]
	v_mfma_f32_16x16x32_bf16 v[24:27], v[144:147], v[200:203], v[24:27]
	v_mfma_f32_16x16x32_bf16 v[20:23], v[152:155], v[200:203], v[20:23]
	s_setprio 0
	s_setprio 1
	v_mfma_f32_16x16x32_bf16 v[48:51], v[156:159], v[172:175], v[48:51]
	v_mfma_f32_16x16x32_bf16 v[44:47], v[164:167], v[172:175], v[44:47]
	v_mfma_f32_16x16x32_bf16 v[32:35], v[156:159], v[180:183], v[32:35]
	v_mfma_f32_16x16x32_bf16 v[28:31], v[164:167], v[180:183], v[28:31]
	v_mfma_f32_16x16x32_bf16 v[16:19], v[156:159], v[188:191], v[16:19]
	v_mfma_f32_16x16x32_bf16 v[12:15], v[164:167], v[188:191], v[12:15]
	v_mfma_f32_16x16x32_bf16 v[8:11], v[156:159], v[196:199], v[8:11]
	v_mfma_f32_16x16x32_bf16 v[4:7], v[164:167], v[196:199], v[4:7]
	v_mfma_f32_16x16x32_bf16 v[48:51], v[160:163], v[176:179], v[48:51]
	v_mfma_f32_16x16x32_bf16 v[44:47], v[168:171], v[176:179], v[44:47]
	v_mfma_f32_16x16x32_bf16 v[32:35], v[160:163], v[184:187], v[32:35]
	v_mfma_f32_16x16x32_bf16 v[28:31], v[168:171], v[184:187], v[28:31]
	v_mfma_f32_16x16x32_bf16 v[16:19], v[160:163], v[192:195], v[16:19]
	v_mfma_f32_16x16x32_bf16 v[12:15], v[168:171], v[192:195], v[12:15]
	v_mfma_f32_16x16x32_bf16 v[8:11], v[160:163], v[200:203], v[8:11]
	v_mfma_f32_16x16x32_bf16 v[4:7], v[168:171], v[200:203], v[4:7]
	s_setprio 0
	s_barrier
	s_add_i32 s47, s47, 2
	s_add_u32 s20, s20, 0x100
	s_addc_u32 s21, s21, 0
	s_add_u32 s45, s45, 0x100
	s_addc_u32 s46, s46, 0
	s_cmp_gt_u32 s47, 29
	s_cbranch_scc0 .LBB0_495
	s_and_b64 vcc, exec, s[8:9]
	s_cbranch_vccz .LBB0_498
	s_barrier

.LBB0_1010:
	s_sleep 1
	s_add_u32 s24, s22, 0xfff80080
	s_addc_u32 s25, s23, -1
	s_add_i32 s49, 0, 0x10000
	s_cmp_eq_u32 s48, 28
	s_cselect_b32 s27, s13, s25
	s_cselect_b32 s26, s19, s24
	s_cselect_b32 s25, s11, s47
	s_cselect_b32 s24, s45, s46
	s_add_i32 s52, 0, 0x14000
	v_add_u32_e32 v144, s49, v219
	v_add_u32_e32 v160, s52, v219
	ds_read_b128 v[116:119], v144
	ds_read_b128 v[124:127], v144 offset:1024
	ds_read_b128 v[132:135], v144 offset:2048
	ds_read_b128 v[144:147], v144 offset:3072
	ds_read_b128 v[148:151], v160
	ds_read_b128 v[152:155], v160 offset:1024
	ds_read_b128 v[156:159], v160 offset:2048
	ds_read_b128 v[160:163], v160 offset:3072
	v_lshl_add_u64 v[204:205], s[22:23], 0, v[192:193]
	s_add_i32 m0, s21, 0xc000
	ds_read_b128 v[164:167], v221
	ds_read_b128 v[168:171], v221 offset:1024
	ds_read_b128 v[172:175], v221 offset:2048
	ds_read_b128 v[176:179], v221 offset:3072
	ds_read_b128 v[180:183], v221 offset:4096
	ds_read_b128 v[184:187], v221 offset:5120
	ds_read_b128 v[196:199], v221 offset:6144
	ds_read_b128 v[200:203], v221 offset:7168
	global_load_lds_dwordx4 v[204:205], off
	v_lshl_add_u64 v[204:205], s[22:23], 0, v[194:195]
	s_add_i32 m0, s21, 0xe000
	s_nop 0
	global_load_lds_dwordx4 v[204:205], off
	s_waitcnt vmcnt(8)
	s_waitcnt lgkmcnt(0)
	s_barrier
	s_setprio 1
	s_waitcnt lgkmcnt(0)
	v_mfma_f32_16x16x32_bf16 v[140:143], v[116:119], v[164:167], v[140:143]
	v_mfma_f32_16x16x32_bf16 v[136:139], v[132:135], v[164:167], v[136:139]
	v_mfma_f32_16x16x32_bf16 v[112:115], v[116:119], v[172:175], v[112:115]
	v_mfma_f32_16x16x32_bf16 v[108:111], v[132:135], v[172:175], v[108:111]
	v_mfma_f32_16x16x32_bf16 v[96:99], v[116:119], v[180:183], v[96:99]
	v_mfma_f32_16x16x32_bf16 v[92:95], v[132:135], v[180:183], v[92:95]
	v_mfma_f32_16x16x32_bf16 v[80:83], v[116:119], v[196:199], v[80:83]
	v_mfma_f32_16x16x32_bf16 v[76:79], v[132:135], v[196:199], v[76:79]
	v_mfma_f32_16x16x32_bf16 v[140:143], v[124:127], v[168:171], v[140:143]
	v_mfma_f32_16x16x32_bf16 v[136:139], v[144:147], v[168:171], v[136:139]
	v_mfma_f32_16x16x32_bf16 v[112:115], v[124:127], v[176:179], v[112:115]
	v_mfma_f32_16x16x32_bf16 v[108:111], v[144:147], v[176:179], v[108:111]
	v_mfma_f32_16x16x32_bf16 v[96:99], v[124:127], v[184:187], v[96:99]
	v_mfma_f32_16x16x32_bf16 v[92:95], v[144:147], v[184:187], v[92:95]
	v_mfma_f32_16x16x32_bf16 v[80:83], v[124:127], v[200:203], v[80:83]
	v_mfma_f32_16x16x32_bf16 v[76:79], v[144:147], v[200:203], v[76:79]
	s_setprio 0
	s_setprio 1
	v_mfma_f32_16x16x32_bf16 v[128:131], v[148:151], v[164:167], v[128:131]
	v_mfma_f32_16x16x32_bf16 v[120:123], v[156:159], v[164:167], v[120:123]
	v_mfma_f32_16x16x32_bf16 v[104:107], v[148:151], v[172:175], v[104:107]
	v_mfma_f32_16x16x32_bf16 v[100:103], v[156:159], v[172:175], v[100:103]
	v_mfma_f32_16x16x32_bf16 v[88:91], v[148:151], v[180:183], v[88:91]
	v_mfma_f32_16x16x32_bf16 v[84:87], v[156:159], v[180:183], v[84:87]
	v_mfma_f32_16x16x32_bf16 v[72:75], v[148:151], v[196:199], v[72:75]
	v_mfma_f32_16x16x32_bf16 v[68:71], v[156:159], v[196:199], v[68:71]
	v_mfma_f32_16x16x32_bf16 v[128:131], v[152:155], v[168:171], v[128:131]
	v_mfma_f32_16x16x32_bf16 v[120:123], v[160:163], v[168:171], v[120:123]
	v_mfma_f32_16x16x32_bf16 v[104:107], v[152:155], v[176:179], v[104:107]
	v_mfma_f32_16x16x32_bf16 v[100:103], v[160:163], v[176:179], v[100:103]
	v_mfma_f32_16x16x32_bf16 v[88:91], v[152:155], v[184:187], v[88:91]
	v_mfma_f32_16x16x32_bf16 v[84:87], v[160:163], v[184:187], v[84:87]
	v_mfma_f32_16x16x32_bf16 v[72:75], v[152:155], v[200:203], v[72:75]
	v_mfma_f32_16x16x32_bf16 v[68:71], v[160:163], v[200:203], v[68:71]
	s_setprio 0
	s_barrier
	s_sleep 1
	s_add_i32 s49, s49, s30
	v_lshl_add_u64 v[204:205], s[24:25], 0, v[2:3]
	s_mov_b32 m0, s49
	ds_read_b128 v[164:167], v221 offset:16384
	ds_read_b128 v[168:171], v221 offset:17408
	ds_read_b128 v[172:175], v221 offset:18432
	ds_read_b128 v[176:179], v221 offset:19456
	ds_read_b128 v[180:183], v221 offset:20480
	ds_read_b128 v[184:187], v221 offset:21504
	ds_read_b128 v[196:199], v221 offset:22528
	ds_read_b128 v[200:203], v221 offset:23552
	global_load_lds_dwordx4 v[204:205], off
	s_add_i32 m0, s49, 0x2000
	s_add_u32 s50, s24, 0x80000
	v_lshl_add_u64 v[206:207], s[24:25], 0, v[190:191]
	s_addc_u32 s51, s25, 0
	s_add_i32 s49, s52, s30
	global_load_lds_dwordx4 v[206:207], off
	v_lshl_add_u64 v[208:209], s[50:51], 0, v[2:3]
	s_mov_b32 m0, s49
	v_lshl_add_u64 v[210:211], s[26:27], 0, v[188:189]
	global_load_lds_dwordx4 v[208:209], off
	v_lshl_add_u64 v[208:209], s[50:51], 0, v[190:191]
	s_add_i32 m0, s49, 0x2000
	s_nop 0
	global_load_lds_dwordx4 v[208:209], off
	v_lshl_add_u64 v[208:209], s[26:27], 0, v[0:1]
	s_mov_b32 m0, s21
	s_nop 0
	global_load_lds_dwordx4 v[208:209], off
	s_mov_b32 m0, s31
	s_nop 0
	global_load_lds_dwordx4 v[210:211], off
	s_waitcnt vmcnt(8)
	s_waitcnt lgkmcnt(0)
	s_barrier
	s_setprio 1
	s_waitcnt lgkmcnt(0)
	v_mfma_f32_16x16x32_bf16 v[64:67], v[116:119], v[164:167], v[64:67]
	v_mfma_f32_16x16x32_bf16 v[60:63], v[132:135], v[164:167], v[60:63]
	v_mfma_f32_16x16x32_bf16 v[48:51], v[116:119], v[172:175], v[48:51]
	v_mfma_f32_16x16x32_bf16 v[44:47], v[132:135], v[172:175], v[44:47]
	v_mfma_f32_16x16x32_bf16 v[32:35], v[116:119], v[180:183], v[32:35]
	v_mfma_f32_16x16x32_bf16 v[28:31], v[132:135], v[180:183], v[28:31]
	v_mfma_f32_16x16x32_bf16 v[16:19], v[116:119], v[196:199], v[16:19]
	v_mfma_f32_16x16x32_bf16 v[12:15], v[132:135], v[196:199], v[12:15]
	v_mfma_f32_16x16x32_bf16 v[64:67], v[124:127], v[168:171], v[64:67]
	v_mfma_f32_16x16x32_bf16 v[60:63], v[144:147], v[168:171], v[60:63]
	v_mfma_f32_16x16x32_bf16 v[48:51], v[124:127], v[176:179], v[48:51]
	v_mfma_f32_16x16x32_bf16 v[44:47], v[144:147], v[176:179], v[44:47]
	v_mfma_f32_16x16x32_bf16 v[32:35], v[124:127], v[184:187], v[32:35]
	v_mfma_f32_16x16x32_bf16 v[28:31], v[144:147], v[184:187], v[28:31]
	v_mfma_f32_16x16x32_bf16 v[16:19], v[124:127], v[200:203], v[16:19]
	v_mfma_f32_16x16x32_bf16 v[12:15], v[144:147], v[200:203], v[12:15]
	s_setprio 0
	s_setprio 1
	v_mfma_f32_16x16x32_bf16 v[56:59], v[148:151], v[164:167], v[56:59]
	v_mfma_f32_16x16x32_bf16 v[52:55], v[156:159], v[164:167], v[52:55]
	v_mfma_f32_16x16x32_bf16 v[40:43], v[148:151], v[172:175], v[40:43]
	v_mfma_f32_16x16x32_bf16 v[36:39], v[156:159], v[172:175], v[36:39]
	v_mfma_f32_16x16x32_bf16 v[24:27], v[148:151], v[180:183], v[24:27]
	v_mfma_f32_16x16x32_bf16 v[20:23], v[156:159], v[180:183], v[20:23]
	v_mfma_f32_16x16x32_bf16 v[8:11], v[148:151], v[196:199], v[8:11]
	v_mfma_f32_16x16x32_bf16 v[4:7], v[156:159], v[196:199], v[4:7]
	v_mfma_f32_16x16x32_bf16 v[56:59], v[152:155], v[168:171], v[56:59]
	v_mfma_f32_16x16x32_bf16 v[52:55], v[160:163], v[168:171], v[52:55]
	v_mfma_f32_16x16x32_bf16 v[40:43], v[152:155], v[176:179], v[40:43]
	v_mfma_f32_16x16x32_bf16 v[36:39], v[160:163], v[176:179], v[36:39]
	v_mfma_f32_16x16x32_bf16 v[24:27], v[152:155], v[184:187], v[24:27]
	v_mfma_f32_16x16x32_bf16 v[20:23], v[160:163], v[184:187], v[20:23]
	v_mfma_f32_16x16x32_bf16 v[8:11], v[152:155], v[200:203], v[8:11]
	v_mfma_f32_16x16x32_bf16 v[4:7], v[160:163], v[200:203], v[4:7]
	s_setprio 0
	s_barrier
	s_sleep 1
	s_add_i32 s49, 0, 0x18000
	s_add_i32 s50, 0, 0x1c000
	v_add_u32_e32 v144, s49, v219
	v_add_u32_e32 v160, s50, v219
	ds_read_b128 v[116:119], v144
	ds_read_b128 v[124:127], v144 offset:1024
	ds_read_b128 v[132:135], v144 offset:2048
	ds_read_b128 v[144:147], v144 offset:3072
	ds_read_b128 v[148:151], v160
	ds_read_b128 v[152:155], v160 offset:1024
	ds_read_b128 v[156:159], v160 offset:2048
	ds_read_b128 v[160:163], v160 offset:3072
	s_add_u32 s26, s26, 0x80000
	s_addc_u32 s27, s27, 0
	s_mov_b32 m0, s35
	v_lshl_add_u64 v[212:213], s[26:27], 0, v[0:1]
	ds_read_b128 v[164:167], v221 offset:32768
	ds_read_b128 v[168:171], v221 offset:33792
	ds_read_b128 v[172:175], v221 offset:34816
	ds_read_b128 v[176:179], v221 offset:35840
	ds_read_b128 v[180:183], v221 offset:36864
	ds_read_b128 v[184:187], v221 offset:37888
	ds_read_b128 v[196:199], v221 offset:38912
	ds_read_b128 v[200:203], v221 offset:39936
	global_load_lds_dwordx4 v[212:213], off
	v_lshl_add_u64 v[212:213], s[26:27], 0, v[188:189]
	s_mov_b32 m0, s40
	s_nop 0
	global_load_lds_dwordx4 v[212:213], off
	s_waitcnt vmcnt(8)
	s_waitcnt lgkmcnt(0)
	s_barrier
	s_setprio 1
	s_waitcnt lgkmcnt(0)
	v_mfma_f32_16x16x32_bf16 v[140:143], v[116:119], v[164:167], v[140:143]
	v_mfma_f32_16x16x32_bf16 v[136:139], v[132:135], v[164:167], v[136:139]
	v_mfma_f32_16x16x32_bf16 v[112:115], v[116:119], v[172:175], v[112:115]
	v_mfma_f32_16x16x32_bf16 v[108:111], v[132:135], v[172:175], v[108:111]
	v_mfma_f32_16x16x32_bf16 v[96:99], v[116:119], v[180:183], v[96:99]
	v_mfma_f32_16x16x32_bf16 v[92:95], v[132:135], v[180:183], v[92:95]
	v_mfma_f32_16x16x32_bf16 v[80:83], v[116:119], v[196:199], v[80:83]
	v_mfma_f32_16x16x32_bf16 v[76:79], v[132:135], v[196:199], v[76:79]
	v_mfma_f32_16x16x32_bf16 v[140:143], v[124:127], v[168:171], v[140:143]
	v_mfma_f32_16x16x32_bf16 v[136:139], v[144:147], v[168:171], v[136:139]
	v_mfma_f32_16x16x32_bf16 v[112:115], v[124:127], v[176:179], v[112:115]
	v_mfma_f32_16x16x32_bf16 v[108:111], v[144:147], v[176:179], v[108:111]
	v_mfma_f32_16x16x32_bf16 v[96:99], v[124:127], v[184:187], v[96:99]
	v_mfma_f32_16x16x32_bf16 v[92:95], v[144:147], v[184:187], v[92:95]
	v_mfma_f32_16x16x32_bf16 v[80:83], v[124:127], v[200:203], v[80:83]
	v_mfma_f32_16x16x32_bf16 v[76:79], v[144:147], v[200:203], v[76:79]
	s_setprio 0
	s_setprio 1
	v_mfma_f32_16x16x32_bf16 v[128:131], v[148:151], v[164:167], v[128:131]
	v_mfma_f32_16x16x32_bf16 v[120:123], v[156:159], v[164:167], v[120:123]
	v_mfma_f32_16x16x32_bf16 v[104:107], v[148:151], v[172:175], v[104:107]
	v_mfma_f32_16x16x32_bf16 v[100:103], v[156:159], v[172:175], v[100:103]
	v_mfma_f32_16x16x32_bf16 v[88:91], v[148:151], v[180:183], v[88:91]
	v_mfma_f32_16x16x32_bf16 v[84:87], v[156:159], v[180:183], v[84:87]
	v_mfma_f32_16x16x32_bf16 v[72:75], v[148:151], v[196:199], v[72:75]
	v_mfma_f32_16x16x32_bf16 v[68:71], v[156:159], v[196:199], v[68:71]
	v_mfma_f32_16x16x32_bf16 v[128:131], v[152:155], v[168:171], v[128:131]
	v_mfma_f32_16x16x32_bf16 v[120:123], v[160:163], v[168:171], v[120:123]
	v_mfma_f32_16x16x32_bf16 v[104:107], v[152:155], v[176:179], v[104:107]
	v_mfma_f32_16x16x32_bf16 v[100:103], v[160:163], v[176:179], v[100:103]
	v_mfma_f32_16x16x32_bf16 v[88:91], v[152:155], v[184:187], v[88:91]
	v_mfma_f32_16x16x32_bf16 v[84:87], v[160:163], v[184:187], v[84:87]
	v_mfma_f32_16x16x32_bf16 v[72:75], v[152:155], v[200:203], v[72:75]
	v_mfma_f32_16x16x32_bf16 v[68:71], v[160:163], v[200:203], v[68:71]
	s_setprio 0
	s_barrier
	s_sleep 1
	s_add_i32 s26, s49, s30
	v_lshl_add_u64 v[204:205], v[204:205], 0, s[66:67]
	s_mov_b32 m0, s26
	ds_read_b128 v[164:167], v221 offset:49152
	ds_read_b128 v[168:171], v221 offset:50176
	ds_read_b128 v[172:175], v221 offset:51200
	ds_read_b128 v[176:179], v221 offset:52224
	ds_read_b128 v[180:183], v221 offset:53248
	ds_read_b128 v[184:187], v221 offset:54272
	ds_read_b128 v[196:199], v221 offset:55296
	ds_read_b128 v[200:203], v221 offset:56320
	global_load_lds_dwordx4 v[204:205], off
	s_add_i32 m0, s26, 0x2000
	s_add_u32 s24, s24, 0x80080
	v_lshl_add_u64 v[204:205], v[206:207], 0, s[66:67]
	s_addc_u32 s25, s25, 0
	s_add_i32 s26, s50, s30
	global_load_lds_dwordx4 v[204:205], off
	v_lshl_add_u64 v[204:205], s[24:25], 0, v[2:3]
	s_mov_b32 m0, s26
	s_nop 0
	global_load_lds_dwordx4 v[204:205], off
	v_lshl_add_u64 v[204:205], s[24:25], 0, v[190:191]
	s_add_i32 m0, s26, 0x2000
	s_nop 0
	global_load_lds_dwordx4 v[204:205], off
	v_lshl_add_u64 v[204:205], v[208:209], 0, s[66:67]
	s_mov_b32 m0, s41
	s_nop 0
	global_load_lds_dwordx4 v[204:205], off
	v_lshl_add_u64 v[204:205], v[210:211], 0, s[66:67]
	s_mov_b32 m0, s42
	s_nop 0
	global_load_lds_dwordx4 v[204:205], off
	s_waitcnt vmcnt(8)
	s_waitcnt lgkmcnt(0)
	s_barrier
	s_setprio 1
	s_waitcnt lgkmcnt(0)
	v_mfma_f32_16x16x32_bf16 v[64:67], v[116:119], v[164:167], v[64:67]
	v_mfma_f32_16x16x32_bf16 v[60:63], v[132:135], v[164:167], v[60:63]
	v_mfma_f32_16x16x32_bf16 v[48:51], v[116:119], v[172:175], v[48:51]
	v_mfma_f32_16x16x32_bf16 v[44:47], v[132:135], v[172:175], v[44:47]
	v_mfma_f32_16x16x32_bf16 v[32:35], v[116:119], v[180:183], v[32:35]
	v_mfma_f32_16x16x32_bf16 v[28:31], v[132:135], v[180:183], v[28:31]
	v_mfma_f32_16x16x32_bf16 v[16:19], v[116:119], v[196:199], v[16:19]
	v_mfma_f32_16x16x32_bf16 v[12:15], v[132:135], v[196:199], v[12:15]
	v_mfma_f32_16x16x32_bf16 v[64:67], v[124:127], v[168:171], v[64:67]
	v_mfma_f32_16x16x32_bf16 v[60:63], v[144:147], v[168:171], v[60:63]
	v_mfma_f32_16x16x32_bf16 v[48:51], v[124:127], v[176:179], v[48:51]
	v_mfma_f32_16x16x32_bf16 v[44:47], v[144:147], v[176:179], v[44:47]
	v_mfma_f32_16x16x32_bf16 v[32:35], v[124:127], v[184:187], v[32:35]
	v_mfma_f32_16x16x32_bf16 v[28:31], v[144:147], v[184:187], v[28:31]
	v_mfma_f32_16x16x32_bf16 v[16:19], v[124:127], v[200:203], v[16:19]
	v_mfma_f32_16x16x32_bf16 v[12:15], v[144:147], v[200:203], v[12:15]
	s_setprio 0
	s_setprio 1
	v_mfma_f32_16x16x32_bf16 v[56:59], v[148:151], v[164:167], v[56:59]
	v_mfma_f32_16x16x32_bf16 v[52:55], v[156:159], v[164:167], v[52:55]
	v_mfma_f32_16x16x32_bf16 v[40:43], v[148:151], v[172:175], v[40:43]
	v_mfma_f32_16x16x32_bf16 v[36:39], v[156:159], v[172:175], v[36:39]
	v_mfma_f32_16x16x32_bf16 v[24:27], v[148:151], v[180:183], v[24:27]
	v_mfma_f32_16x16x32_bf16 v[20:23], v[156:159], v[180:183], v[20:23]
	v_mfma_f32_16x16x32_bf16 v[8:11], v[148:151], v[196:199], v[8:11]
	v_mfma_f32_16x16x32_bf16 v[4:7], v[156:159], v[196:199], v[4:7]
	v_mfma_f32_16x16x32_bf16 v[56:59], v[152:155], v[168:171], v[56:59]
	v_mfma_f32_16x16x32_bf16 v[52:55], v[160:163], v[168:171], v[52:55]
	v_mfma_f32_16x16x32_bf16 v[40:43], v[152:155], v[176:179], v[40:43]
	v_mfma_f32_16x16x32_bf16 v[36:39], v[160:163], v[176:179], v[36:39]
	v_mfma_f32_16x16x32_bf16 v[24:27], v[152:155], v[184:187], v[24:27]
	v_mfma_f32_16x16x32_bf16 v[20:23], v[160:163], v[184:187], v[20:23]
	v_mfma_f32_16x16x32_bf16 v[8:11], v[152:155], v[200:203], v[8:11]
	v_mfma_f32_16x16x32_bf16 v[4:7], v[160:163], v[200:203], v[4:7]
	s_setprio 0
	s_barrier
	s_add_i32 s48, s48, 2
	s_add_u32 s22, s22, 0x100
	s_addc_u32 s23, s23, 0
	s_add_u32 s46, s46, 0x100
	s_addc_u32 s47, s47, 0
	s_cmp_gt_u32 s48, 29
	s_cbranch_scc0 .LBB0_1010
	s_and_b64 vcc, exec, s[8:9]
	s_cbranch_vccz .LBB0_1013
	s_barrier
